# P6 GELU epilogue: sign select replaced by fma(-|v|, g, max(v,0)) and |v| folded into the first fma (same math, fewer VALU instructions)
# speedup vs baseline: 1.0098x; 1.0098x over previous
; __device__ __forceinline__ float dot4(f32x4 v) { return (v[0] * v[0] + v[1] * v[1]) + (v[2] * v[2] + v[3] * v[3]); }
; __device__ __forceinline__ u32x2 pack4(f32x4 v) { u32x2 w; w.x = cvt_pk_bf16(v[0], v[1]); w.y = cvt_pk_bf16(v[2], v[3]); return w; }
; __device__ __forceinline__ float quad_sum(float s) { s += __shfl_xor(s, 16); s += __shfl_xor(s, 32); return s; }
; __device__ __forceinline__ f32x4 gelu4(f32x4 v) { f32x2 a = gelu_pk((f32x2){v[0], v[1]}), b = gelu_pk((f32x2){v[2], v[3]}); return (f32x4){a.x, a.y, b.x, b.y}; }
; __device__ __forceinline__ f32x2 gelu_pk(f32x2 v) {
;     const f32x2 av = __builtin_elementwise_abs(v), d = av * 0.2316418882f + 1.0f;
;     f32x2 t; t.x = __builtin_amdgcn_rcpf(d.x); t.y = __builtin_amdgcn_rcpf(d.y);
;     f32x2 q = t * 0.5307027145f + (-0.7265760135f); q = q * t + 0.7107068705f; q = q * t + (-0.142248368f); q = q * t + 0.127414796f; q = q * t;
;     const f32x2 s = (v * v) * (-0.72134752044f);
;     f32x2 e; e.x = __builtin_amdgcn_exp2f(s.x); e.y = __builtin_amdgcn_exp2f(s.y);
;     const f32x2 m = v * (q * e), r = v - m;
;     f32x2 o; o.x = v.x < 0.f ? m.x : r.x; o.y = v.y < 0.f ? m.y : r.y; return o;
; }
; template <int EK>
; __device__ __forceinline__ void epi_tile(const f32x4 (&acc)[2][2][4][2], const Unit& u, int wr, int wc, int fr, int fq, const EpiArgs& E, const LAS float* rt) {
;     ...
;             } else if (EK == EK_GELU) {
;                 const float r = rr[ai][m]; float ss = 0.f;
; #pragma unroll
;                 for (int bj = 0; bj < 2; ++bj) { const int col = u.pn * BM + bj * HALF + wc * 32 + fq * 8;
;                     const f32x4 z0 = gelu4(acc[ai][bj][m][0] * r), z1 = gelu4(acc[ai][bj][m][1] * r); ss += dot4(z0) + dot4(z1);
;                     const u32x2 lo = pack4(z0), hi = pack4(z1);
;                     *(u32x4*)(E.ob + (size_t)row * E.ldb + col) = (u32x4){lo.x, lo.y, hi.x, hi.y}; }
;                 if (u.pn >= 4) { ss = quad_sum(ss); if (fq == 0) E.stOut[(size_t)row * 16 + (u.pn - 4) * 4 + wc] = ss; }
.LBB0_932:
	v_lshl_add_u32 v146, s84, 10, v161
	ds_read2_b32 v[156:157], v146 offset1:16
	ds_read2_b32 v[154:155], v146 offset0:32 offset1:48
	ds_read2_b32 v[152:153], v146 offset0:128 offset1:144
	ds_read2_b32 v[148:149], v146 offset0:160 offset1:176
	v_lshl_add_u32 v150, s22, 8, v1
	s_waitcnt lgkmcnt(0)
	v_pk_mul_f32 v[166:167], v[110:111], v[156:157] op_sel_hi:[1,0]
	v_pk_mul_f32 v[170:171], v[112:113], v[156:157] op_sel_hi:[1,0]
	v_fma_f32 v158, |v166|, s40, 1.0
	v_fma_f32 v159, |v167|, s40, 1.0
	v_pk_mul_f32 v[174:175], v[166:167], v[166:167]
	v_rcp_f32_e32 v168, v158
	v_rcp_f32_e32 v169, v159
	v_mov_b64_e32 v[158:159], s[44:45]
	v_pk_mul_f32 v[174:175], v[174:175], s[58:59] op_sel_hi:[1,0]
	v_pk_fma_f32 v[172:173], v[168:169], s[42:43], v[158:159] op_sel_hi:[1,0,0]
	v_exp_f32_e32 v174, v174
	v_pk_fma_f32 v[172:173], v[168:169], v[172:173], s[52:53] op_sel_hi:[1,1,0]
	v_exp_f32_e32 v175, v175
	v_pk_fma_f32 v[172:173], v[168:169], v[172:173], s[54:55] op_sel_hi:[1,1,0]
	v_pk_fma_f32 v[172:173], v[168:169], v[172:173], s[56:57] op_sel_hi:[1,1,0]
	v_fma_f32 v176, |v170|, s40, 1.0
	v_fma_f32 v177, |v171|, s40, 1.0
	v_pk_mul_f32 v[168:169], v[168:169], v[172:173]
	v_rcp_f32_e32 v176, v176
	v_rcp_f32_e32 v177, v177
	v_pk_mul_f32 v[168:169], v[174:175], v[168:169]
	v_max_f32_e32 v174, 0, v166
	v_max_f32_e32 v175, 0, v167
	v_fma_f32 v165, -|v166|, v168, v174
	v_fma_f32 v166, -|v167|, v169, v175
	v_pk_mul_f32 v[172:173], v[170:171], v[170:171]
	v_pk_mul_f32 v[172:173], v[172:173], s[58:59] op_sel_hi:[1,0]
	v_ashrrev_i32_e32 v151, 31, v150
	v_pk_fma_f32 v[168:169], v[176:177], s[42:43], v[158:159] op_sel_hi:[1,0,0]
	v_exp_f32_e32 v172, v172
	v_pk_fma_f32 v[168:169], v[176:177], v[168:169], s[52:53] op_sel_hi:[1,1,0]
	v_exp_f32_e32 v173, v173
	v_pk_fma_f32 v[168:169], v[176:177], v[168:169], s[54:55] op_sel_hi:[1,1,0]
	v_pk_mul_f32 v[174:175], v[106:107], v[156:157] op_sel_hi:[1,0]
	v_pk_fma_f32 v[168:169], v[176:177], v[168:169], s[56:57] op_sel_hi:[1,1,0]
	v_pk_mul_f32 v[168:169], v[176:177], v[168:169]
	v_fma_f32 v176, |v174|, s40, 1.0
	v_fma_f32 v177, |v175|, s40, 1.0
	v_pk_mul_f32 v[168:169], v[172:173], v[168:169]
	v_rcp_f32_e32 v176, v176
	v_rcp_f32_e32 v177, v177
	v_max_f32_e32 v172, 0, v170
	v_max_f32_e32 v173, 0, v171
	v_fma_f32 v167, -|v170|, v168, v172
	v_fma_f32 v168, -|v171|, v169, v173
	v_pk_mul_f32 v[178:179], v[174:175], v[174:175]
	v_pk_fma_f32 v[170:171], v[176:177], s[42:43], v[158:159] op_sel_hi:[1,0,0]
	v_pk_mul_f32 v[178:179], v[178:179], s[58:59] op_sel_hi:[1,0]
	v_pk_mul_f32 v[172:173], v[108:109], v[156:157] op_sel_hi:[1,0]
	v_pk_fma_f32 v[170:171], v[176:177], v[170:171], s[52:53] op_sel_hi:[1,1,0]
	v_exp_f32_e32 v178, v178
	v_exp_f32_e32 v179, v179
	v_pk_fma_f32 v[170:171], v[176:177], v[170:171], s[54:55] op_sel_hi:[1,1,0]
	v_fma_f32 v180, |v172|, s40, 1.0
	v_fma_f32 v181, |v173|, s40, 1.0
	v_pk_fma_f32 v[170:171], v[176:177], v[170:171], s[56:57] op_sel_hi:[1,1,0]
	v_rcp_f32_e32 v180, v180
	v_rcp_f32_e32 v181, v181
	v_pk_mul_f32 v[170:171], v[176:177], v[170:171]
	v_pk_mul_f32 v[170:171], v[178:179], v[170:171]
	v_pk_mul_f32 v[176:177], v[172:173], v[172:173]
	v_max_f32_e32 v178, 0, v174
	v_max_f32_e32 v179, 0, v175
	v_fma_f32 v169, -|v174|, v170, v178
	v_fma_f32 v170, -|v175|, v171, v179
	v_pk_mul_f32 v[176:177], v[176:177], s[58:59] op_sel_hi:[1,0]
	v_pk_fma_f32 v[174:175], v[180:181], s[42:43], v[158:159] op_sel_hi:[1,0,0]
	v_exp_f32_e32 v176, v176
	v_pk_fma_f32 v[174:175], v[180:181], v[174:175], s[52:53] op_sel_hi:[1,1,0]
	v_exp_f32_e32 v177, v177
	v_pk_fma_f32 v[174:175], v[180:181], v[174:175], s[54:55] op_sel_hi:[1,1,0]
	v_lshl_or_b32 v146, s26, 8, v162
	v_pk_fma_f32 v[174:175], v[180:181], v[174:175], s[56:57] op_sel_hi:[1,1,0]
	v_pk_mul_f32 v[174:175], v[180:181], v[174:175]
	v_pk_mul_f32 v[180:181], v[78:79], v[156:157] op_sel_hi:[1,0]
	v_pk_mul_f32 v[174:175], v[176:177], v[174:175]
	v_fma_f32 v182, |v180|, s40, 1.0
	v_fma_f32 v183, |v181|, s40, 1.0
	v_pk_mul_f32 v[176:177], v[172:173], v[174:175]
	v_rcp_f32_e32 v182, v182
	v_rcp_f32_e32 v183, v183
	v_pk_fma_f32 v[174:175], v[172:173], v[174:175], v[172:173] neg_lo:[1,0,0] neg_hi:[1,0,0]
	v_cmp_gt_f32_e32 vcc, 0, v172
	v_lshlrev_b64 v[178:179], 12, v[150:151]
	v_lshl_add_u64 v[178:179], s[64:65], 0, v[178:179]
	v_cndmask_b32_e32 v171, v174, v176, vcc
	v_cmp_gt_f32_e32 vcc, 0, v173
	v_ashrrev_i32_e32 v147, 31, v146
	v_cvt_pk_bf16_f32 v174, v165, v166
	v_lshl_add_u64 v[184:185], v[146:147], 1, v[178:179]
	v_cndmask_b32_e32 v172, v175, v177, vcc
	v_cvt_pk_bf16_f32 v175, v167, v168
	v_pk_mul_f32 v[178:179], v[180:181], v[180:181]
	v_cvt_pk_bf16_f32 v176, v169, v170
	v_cvt_pk_bf16_f32 v177, v171, v172
	global_store_dwordx4 v[184:185], v[174:177], off
	v_pk_mul_f32 v[178:179], v[178:179], s[58:59] op_sel_hi:[1,0]
	v_cmp_gt_f32_e32 vcc, 0, v180
	v_pk_fma_f32 v[174:175], v[182:183], s[42:43], v[158:159] op_sel_hi:[1,0,0]
	v_pk_mul_f32 v[176:177], v[80:81], v[156:157] op_sel_hi:[1,0]
	v_pk_fma_f32 v[174:175], v[182:183], v[174:175], s[52:53] op_sel_hi:[1,1,0]
	v_exp_f32_e32 v178, v178
	v_exp_f32_e32 v179, v179
; __device__ __forceinline__ float dot4(f32x4 v) { return (v[0] * v[0] + v[1] * v[1]) + (v[2] * v[2] + v[3] * v[3]); }
; __device__ __forceinline__ u32x2 pack4(f32x4 v) { u32x2 w; w.x = cvt_pk_bf16(v[0], v[1]); w.y = cvt_pk_bf16(v[2], v[3]); return w; }
; __device__ __forceinline__ float quad_sum(float s) { s += __shfl_xor(s, 16); s += __shfl_xor(s, 32); return s; }
; __device__ __forceinline__ f32x4 gelu4(f32x4 v) { f32x2 a = gelu_pk((f32x2){v[0], v[1]}), b = gelu_pk((f32x2){v[2], v[3]}); return (f32x4){a.x, a.y, b.x, b.y}; }
; __device__ __forceinline__ f32x2 gelu_pk(f32x2 v) {
;     const f32x2 av = __builtin_elementwise_abs(v), d = av * 0.2316418882f + 1.0f;
;     f32x2 t; t.x = __builtin_amdgcn_rcpf(d.x); t.y = __builtin_amdgcn_rcpf(d.y);
;     f32x2 q = t * 0.5307027145f + (-0.7265760135f); q = q * t + 0.7107068705f; q = q * t + (-0.142248368f); q = q * t + 0.127414796f; q = q * t;
;     const f32x2 s = (v * v) * (-0.72134752044f);
;     f32x2 e; e.x = __builtin_amdgcn_exp2f(s.x); e.y = __builtin_amdgcn_exp2f(s.y);
;     const f32x2 m = v * (q * e), r = v - m;
;     f32x2 o; o.x = v.x < 0.f ? m.x : r.x; o.y = v.y < 0.f ? m.y : r.y; return o;
; }
; template <int EK>
; __device__ __forceinline__ void epi_tile(const f32x4 (&acc)[2][2][4][2], const Unit& u, int wr, int wc, int fr, int fq, const EpiArgs& E, const LAS float* rt) {
;     ...
;             } else if (EK == EK_GELU) {
;                 const float r = rr[ai][m]; float ss = 0.f;
; #pragma unroll
;                 for (int bj = 0; bj < 2; ++bj) { const int col = u.pn * BM + bj * HALF + wc * 32 + fq * 8;
;                     const f32x4 z0 = gelu4(acc[ai][bj][m][0] * r), z1 = gelu4(acc[ai][bj][m][1] * r); ss += dot4(z0) + dot4(z1);
;                     const u32x2 lo = pack4(z0), hi = pack4(z1);
;                     *(u32x4*)(E.ob + (size_t)row * E.ldb + col) = (u32x4){lo.x, lo.y, hi.x, hi.y}; }
;                 if (u.pn >= 4) { ss = quad_sum(ss); if (fq == 0) E.stOut[(size_t)row * 16 + (u.pn - 4) * 4 + wc] = ss; }
	v_pk_fma_f32 v[174:175], v[182:183], v[174:175], s[54:55] op_sel_hi:[1,1,0]
	v_pk_fma_f32 v[174:175], v[182:183], v[174:175], s[56:57] op_sel_hi:[1,1,0]
	v_fma_f32 v186, |v176|, s40, 1.0
	v_fma_f32 v187, |v177|, s40, 1.0
	v_pk_mul_f32 v[174:175], v[182:183], v[174:175]
	v_rcp_f32_e32 v186, v186
	v_rcp_f32_e32 v187, v187
	v_pk_mul_f32 v[174:175], v[178:179], v[174:175]
	v_pk_mul_f32 v[182:183], v[176:177], v[176:177]
	v_pk_mul_f32 v[178:179], v[180:181], v[174:175]
	v_pk_fma_f32 v[174:175], v[180:181], v[174:175], v[180:181] neg_lo:[1,0,0] neg_hi:[1,0,0]
	s_cmp_gt_i32 s26, 3
	v_cndmask_b32_e32 v173, v174, v178, vcc
	v_cmp_gt_f32_e32 vcc, 0, v181
	v_pk_mul_f32 v[180:181], v[182:183], s[58:59] op_sel_hi:[1,0]
	v_pk_mul_f32 v[182:183], v[74:75], v[156:157] op_sel_hi:[1,0]
	v_cndmask_b32_e32 v174, v175, v179, vcc
	v_pk_fma_f32 v[178:179], v[186:187], s[42:43], v[158:159] op_sel_hi:[1,0,0]
	v_exp_f32_e32 v180, v180
	v_pk_fma_f32 v[178:179], v[186:187], v[178:179], s[52:53] op_sel_hi:[1,1,0]
	v_exp_f32_e32 v181, v181
	v_pk_fma_f32 v[178:179], v[186:187], v[178:179], s[54:55] op_sel_hi:[1,1,0]
	v_pk_fma_f32 v[178:179], v[186:187], v[178:179], s[56:57] op_sel_hi:[1,1,0]
	v_pk_mul_f32 v[188:189], v[182:183], v[182:183]
	v_pk_mul_f32 v[178:179], v[186:187], v[178:179]
	v_fma_f32 v186, |v182|, s40, 1.0
	v_fma_f32 v187, |v183|, s40, 1.0
	v_pk_mul_f32 v[178:179], v[180:181], v[178:179]
	v_rcp_f32_e32 v186, v186
	v_rcp_f32_e32 v187, v187
	v_max_f32_e32 v180, 0, v176
	v_max_f32_e32 v181, 0, v177
	v_fma_f32 v175, -|v176|, v178, v180
	v_fma_f32 v176, -|v177|, v179, v181
	v_pk_mul_f32 v[188:189], v[188:189], s[58:59] op_sel_hi:[1,0]
	v_exp_f32_e32 v188, v188
	v_exp_f32_e32 v189, v189
	v_pk_fma_f32 v[180:181], v[186:187], s[42:43], v[158:159] op_sel_hi:[1,0,0]
	v_pk_mul_f32 v[178:179], v[76:77], v[156:157] op_sel_hi:[1,0]
	v_pk_fma_f32 v[180:181], v[186:187], v[180:181], s[52:53] op_sel_hi:[1,1,0]
	v_pk_fma_f32 v[180:181], v[186:187], v[180:181], s[54:55] op_sel_hi:[1,1,0]
	v_pk_fma_f32 v[180:181], v[186:187], v[180:181], s[56:57] op_sel_hi:[1,1,0]
	v_fma_f32 v190, |v178|, s40, 1.0
	v_fma_f32 v191, |v179|, s40, 1.0
	v_pk_mul_f32 v[180:181], v[186:187], v[180:181]
	v_rcp_f32_e32 v190, v190
	v_rcp_f32_e32 v191, v191
	v_pk_mul_f32 v[180:181], v[188:189], v[180:181]
	v_max_f32_e32 v188, 0, v182
	v_max_f32_e32 v189, 0, v183
	v_fma_f32 v156, -|v182|, v180, v188
	v_fma_f32 v177, -|v183|, v181, v189
	v_pk_mul_f32 v[186:187], v[178:179], v[178:179]
	v_pk_fma_f32 v[158:159], v[190:191], s[42:43], v[158:159] op_sel_hi:[1,0,0]
	s_cselect_b64 s[78:79], -1, 0
	v_pk_mul_f32 v[180:181], v[186:187], s[58:59] op_sel_hi:[1,0]
	v_pk_fma_f32 v[158:159], v[190:191], v[158:159], s[52:53] op_sel_hi:[1,1,0]
	v_exp_f32_e32 v180, v180
	v_exp_f32_e32 v181, v181
	v_pk_fma_f32 v[158:159], v[190:191], v[158:159], s[54:55] op_sel_hi:[1,1,0]
	s_lshl_b32 s10, s26, 2
	v_pk_fma_f32 v[158:159], v[190:191], v[158:159], s[56:57] op_sel_hi:[1,1,0]
	s_add_i32 s76, s10, -16
	v_pk_mul_f32 v[158:159], v[190:191], v[158:159]
	v_pk_mul_f32 v[158:159], v[180:181], v[158:159]
	s_ashr_i32 s77, s76, 31
	v_max_f32_e32 v180, 0, v178
	v_max_f32_e32 v181, 0, v179
	v_fma_f32 v158, -|v178|, v158, v180
	v_fma_f32 v159, -|v179|, v159, v181
	s_cmp_lt_i32 s26, 4
	v_cvt_pk_bf16_f32 v178, v173, v174
	v_cvt_pk_bf16_f32 v179, v175, v176
	v_cvt_pk_bf16_f32 v180, v156, v177
	s_nop 1
	v_cvt_pk_bf16_f32 v181, v158, v159
	global_store_dwordx4 v[184:185], v[178:181], off offset:256
	s_cbranch_scc1 .LBB0_936
	v_mul_f32_e32 v166, v166, v166
	v_fmac_f32_e32 v166, v165, v165
	v_mul_f32_e32 v165, v168, v168
	v_fmac_f32_e32 v165, v167, v167
	v_add_f32_e32 v165, v166, v165
	v_mul_f32_e32 v166, v170, v170
	v_mul_f32_e32 v167, v172, v172
	v_fmac_f32_e32 v166, v169, v169
	v_fmac_f32_e32 v167, v171, v171
	v_add_f32_e32 v166, v166, v167
	v_add_f32_e32 v165, v165, v166
	v_mul_f32_e32 v166, v174, v174
	v_mul_f32_e32 v167, v176, v176
	v_fmac_f32_e32 v166, v173, v173
	v_fmac_f32_e32 v167, v175, v175
	v_add_f32_e32 v166, v166, v167
	v_mul_f32_e32 v167, v177, v177
	v_fmac_f32_e32 v167, v156, v156
	v_mul_f32_e32 v156, v159, v159
	v_and_b32_e32 v159, 64, v164
	v_fmac_f32_e32 v156, v158, v158
	v_xor_b32_e32 v158, 16, v164
	v_add_u32_e32 v159, 64, v159
	v_add_f32_e32 v156, v167, v156
	v_cmp_lt_i32_e32 vcc, v158, v159
	v_add_f32_e32 v156, v166, v156
	v_add_f32_e32 v156, v165, v156
	v_cndmask_b32_e32 v158, v164, v158, vcc
	v_lshlrev_b32_e32 v158, 2, v158
	ds_bpermute_b32 v158, v158, v156
	s_waitcnt lgkmcnt(0)
	v_add_f32_e32 v156, v156, v158
	v_xor_b32_e32 v158, 32, v164
	v_cmp_lt_i32_e32 vcc, v158, v159
	s_nop 1
	v_cndmask_b32_e32 v158, v164, v158, vcc
	v_lshlrev_b32_e32 v158, 2, v158
	ds_bpermute_b32 v158, v158, v156
	s_and_saveexec_b64 s[10:11], s[4:5]
	s_cbranch_execz .LBB0_935
	v_lshlrev_b64 v[166:167], 6, v[150:151]
	v_lshl_add_u64 v[166:167], s[18:19], 0, v[166:167]
	v_lshl_add_u64 v[166:167], s[76:77], 2, v[166:167]
	s_lshl_b32 s14, s59, 2
	v_lshl_add_u64 v[166:167], v[166:167], 0, s[14:15]
	s_waitcnt lgkmcnt(0)
	v_add_f32_e32 v151, v156, v158
	global_store_dword v[166:167], v151, off

; __device__ __forceinline__ float dot4(f32x4 v) { return (v[0] * v[0] + v[1] * v[1]) + (v[2] * v[2] + v[3] * v[3]); }
; __device__ __forceinline__ u32x2 pack4(f32x4 v) { u32x2 w; w.x = cvt_pk_bf16(v[0], v[1]); w.y = cvt_pk_bf16(v[2], v[3]); return w; }
; __device__ __forceinline__ float quad_sum(float s) { s += __shfl_xor(s, 16); s += __shfl_xor(s, 32); return s; }
; __device__ __forceinline__ f32x4 gelu4(f32x4 v) { f32x2 a = gelu_pk((f32x2){v[0], v[1]}), b = gelu_pk((f32x2){v[2], v[3]}); return (f32x4){a.x, a.y, b.x, b.y}; }
; __device__ __forceinline__ f32x2 gelu_pk(f32x2 v) {
;     const f32x2 av = __builtin_elementwise_abs(v), d = av * 0.2316418882f + 1.0f;
;     f32x2 t; t.x = __builtin_amdgcn_rcpf(d.x); t.y = __builtin_amdgcn_rcpf(d.y);
;     f32x2 q = t * 0.5307027145f + (-0.7265760135f); q = q * t + 0.7107068705f; q = q * t + (-0.142248368f); q = q * t + 0.127414796f; q = q * t;
;     const f32x2 s = (v * v) * (-0.72134752044f);
;     f32x2 e; e.x = __builtin_amdgcn_exp2f(s.x); e.y = __builtin_amdgcn_exp2f(s.y);
;     const f32x2 m = v * (q * e), r = v - m;
;     f32x2 o; o.x = v.x < 0.f ? m.x : r.x; o.y = v.y < 0.f ? m.y : r.y; return o;
; }
; template <int EK>
; __device__ __forceinline__ void epi_tile(const f32x4 (&acc)[2][2][4][2], const Unit& u, int wr, int wc, int fr, int fq, const EpiArgs& E, const LAS float* rt) {
;     ...
;             } else if (EK == EK_GELU) {
;                 const float r = rr[ai][m]; float ss = 0.f;
; #pragma unroll
;                 for (int bj = 0; bj < 2; ++bj) { const int col = u.pn * BM + bj * HALF + wc * 32 + fq * 8;
;                     const f32x4 z0 = gelu4(acc[ai][bj][m][0] * r), z1 = gelu4(acc[ai][bj][m][1] * r); ss += dot4(z0) + dot4(z1);
;                     const u32x2 lo = pack4(z0), hi = pack4(z1);
;                     *(u32x4*)(E.ob + (size_t)row * E.ldb + col) = (u32x4){lo.x, lo.y, hi.x, hi.y}; }
;                 if (u.pn >= 4) { ss = quad_sum(ss); if (fq == 0) E.stOut[(size_t)row * 16 + (u.pn - 4) * 4 + wc] = ss; }
.LBB0_936:
	v_mov_b32_e32 v176, v157
	v_pk_mul_f32 v[166:167], v[102:103], v[176:177] op_sel_hi:[1,0]
	v_pk_mul_f32 v[170:171], v[104:105], v[176:177] op_sel_hi:[1,0]
	s_waitcnt lgkmcnt(0)
	v_fma_f32 v158, |v166|, s40, 1.0
	v_fma_f32 v159, |v167|, s40, 1.0
	v_pk_mul_f32 v[174:175], v[166:167], v[166:167]
	v_rcp_f32_e32 v168, v158
	v_rcp_f32_e32 v169, v159
	v_mov_b64_e32 v[158:159], s[44:45]
	v_pk_mul_f32 v[174:175], v[174:175], s[58:59] op_sel_hi:[1,0]
	v_pk_fma_f32 v[172:173], v[168:169], s[42:43], v[158:159] op_sel_hi:[1,0,0]
	v_exp_f32_e32 v174, v174
	v_pk_fma_f32 v[172:173], v[168:169], v[172:173], s[52:53] op_sel_hi:[1,1,0]
	v_exp_f32_e32 v175, v175
	v_pk_fma_f32 v[172:173], v[168:169], v[172:173], s[54:55] op_sel_hi:[1,1,0]
	v_pk_fma_f32 v[172:173], v[168:169], v[172:173], s[56:57] op_sel_hi:[1,1,0]
	v_fma_f32 v178, |v170|, s40, 1.0
	v_fma_f32 v179, |v171|, s40, 1.0
	v_pk_mul_f32 v[168:169], v[168:169], v[172:173]
	v_rcp_f32_e32 v178, v178
	v_rcp_f32_e32 v179, v179
	v_pk_mul_f32 v[168:169], v[174:175], v[168:169]
	v_max_f32_e32 v174, 0, v166
	v_max_f32_e32 v175, 0, v167
	v_fma_f32 v151, -|v166|, v168, v174
	v_fma_f32 v165, -|v167|, v169, v175
	v_pk_mul_f32 v[172:173], v[170:171], v[170:171]
	v_pk_fma_f32 v[166:167], v[178:179], s[42:43], v[158:159] op_sel_hi:[1,0,0]
	v_or_b32_e32 v156, 16, v150
	v_pk_mul_f32 v[168:169], v[172:173], s[58:59] op_sel_hi:[1,0]
	v_pk_fma_f32 v[166:167], v[178:179], v[166:167], s[52:53] op_sel_hi:[1,1,0]
	v_exp_f32_e32 v168, v168
	v_exp_f32_e32 v169, v169
	v_pk_mul_f32 v[172:173], v[98:99], v[176:177] op_sel_hi:[1,0]
	v_pk_fma_f32 v[166:167], v[178:179], v[166:167], s[54:55] op_sel_hi:[1,1,0]
	v_pk_fma_f32 v[166:167], v[178:179], v[166:167], s[56:57] op_sel_hi:[1,1,0]
	v_fma_f32 v174, |v172|, s40, 1.0
	v_fma_f32 v175, |v173|, s40, 1.0
	v_pk_mul_f32 v[166:167], v[178:179], v[166:167]
	v_rcp_f32_e32 v174, v174
	v_rcp_f32_e32 v175, v175
	v_pk_mul_f32 v[166:167], v[168:169], v[166:167]
	v_max_f32_e32 v168, 0, v170
	v_max_f32_e32 v169, 0, v171
	v_fma_f32 v166, -|v170|, v166, v168
	v_fma_f32 v167, -|v171|, v167, v169
	v_pk_mul_f32 v[178:179], v[172:173], v[172:173]
	v_pk_mul_f32 v[170:171], v[100:101], v[176:177] op_sel_hi:[1,0]
	v_pk_mul_f32 v[178:179], v[178:179], s[58:59] op_sel_hi:[1,0]
	v_pk_fma_f32 v[168:169], v[174:175], s[42:43], v[158:159] op_sel_hi:[1,0,0]
	v_exp_f32_e32 v178, v178
	v_pk_fma_f32 v[168:169], v[174:175], v[168:169], s[52:53] op_sel_hi:[1,1,0]
	v_exp_f32_e32 v179, v179
	v_pk_fma_f32 v[168:169], v[174:175], v[168:169], s[54:55] op_sel_hi:[1,1,0]
	v_fma_f32 v180, |v170|, s40, 1.0
	v_fma_f32 v181, |v171|, s40, 1.0
	v_pk_fma_f32 v[168:169], v[174:175], v[168:169], s[56:57] op_sel_hi:[1,1,0]
	v_rcp_f32_e32 v180, v180
	v_rcp_f32_e32 v181, v181
	v_pk_mul_f32 v[168:169], v[174:175], v[168:169]
	v_pk_mul_f32 v[168:169], v[178:179], v[168:169]
	v_pk_mul_f32 v[174:175], v[170:171], v[170:171]
	v_max_f32_e32 v178, 0, v172
	v_max_f32_e32 v179, 0, v173
	v_fma_f32 v168, -|v172|, v168, v178
	v_fma_f32 v169, -|v173|, v169, v179
	v_pk_mul_f32 v[174:175], v[174:175], s[58:59] op_sel_hi:[1,0]
	v_pk_fma_f32 v[172:173], v[180:181], s[42:43], v[158:159] op_sel_hi:[1,0,0]
	v_exp_f32_e32 v174, v174
	v_pk_fma_f32 v[172:173], v[180:181], v[172:173], s[52:53] op_sel_hi:[1,1,0]
	v_exp_f32_e32 v175, v175
	v_pk_fma_f32 v[172:173], v[180:181], v[172:173], s[54:55] op_sel_hi:[1,1,0]
	v_ashrrev_i32_e32 v157, 31, v156
	v_pk_fma_f32 v[172:173], v[180:181], v[172:173], s[56:57] op_sel_hi:[1,1,0]
	v_pk_mul_f32 v[172:173], v[180:181], v[172:173]
	v_pk_mul_f32 v[180:181], v[70:71], v[176:177] op_sel_hi:[1,0]
	v_pk_mul_f32 v[172:173], v[174:175], v[172:173]
	v_fma_f32 v182, |v180|, s40, 1.0
	v_fma_f32 v183, |v181|, s40, 1.0
	v_pk_mul_f32 v[174:175], v[170:171], v[172:173]
	v_rcp_f32_e32 v182, v182
	v_rcp_f32_e32 v183, v183
	v_pk_fma_f32 v[172:173], v[170:171], v[172:173], v[170:171] neg_lo:[1,0,0] neg_hi:[1,0,0]
	v_cmp_gt_f32_e32 vcc, 0, v170
	v_lshlrev_b64 v[178:179], 12, v[156:157]
	v_lshl_add_u64 v[178:179], s[64:65], 0, v[178:179]
	v_cndmask_b32_e32 v170, v172, v174, vcc
	v_cmp_gt_f32_e32 vcc, 0, v171
	v_cvt_pk_bf16_f32 v172, v151, v165
	v_lshl_add_u64 v[184:185], v[146:147], 1, v[178:179]
	v_pk_mul_f32 v[178:179], v[180:181], v[180:181]
	v_cndmask_b32_e32 v171, v173, v175, vcc
	v_cvt_pk_bf16_f32 v173, v166, v167
	v_cvt_pk_bf16_f32 v174, v168, v169
	v_cvt_pk_bf16_f32 v175, v170, v171
	global_store_dwordx4 v[184:185], v[172:175], off
	v_pk_mul_f32 v[178:179], v[178:179], s[58:59] op_sel_hi:[1,0]
	v_cmp_gt_f32_e32 vcc, 0, v180
	v_pk_fma_f32 v[172:173], v[182:183], s[42:43], v[158:159] op_sel_hi:[1,0,0]
	v_pk_mul_f32 v[174:175], v[72:73], v[176:177] op_sel_hi:[1,0]
	v_pk_fma_f32 v[172:173], v[182:183], v[172:173], s[52:53] op_sel_hi:[1,1,0]
	v_exp_f32_e32 v178, v178
	v_exp_f32_e32 v179, v179
	v_pk_fma_f32 v[172:173], v[182:183], v[172:173], s[54:55] op_sel_hi:[1,1,0]
	v_pk_fma_f32 v[172:173], v[182:183], v[172:173], s[56:57] op_sel_hi:[1,1,0]
	v_fma_f32 v186, |v174|, s40, 1.0
	v_fma_f32 v187, |v175|, s40, 1.0
; __device__ __forceinline__ float dot4(f32x4 v) { return (v[0] * v[0] + v[1] * v[1]) + (v[2] * v[2] + v[3] * v[3]); }
; __device__ __forceinline__ u32x2 pack4(f32x4 v) { u32x2 w; w.x = cvt_pk_bf16(v[0], v[1]); w.y = cvt_pk_bf16(v[2], v[3]); return w; }
; __device__ __forceinline__ float quad_sum(float s) { s += __shfl_xor(s, 16); s += __shfl_xor(s, 32); return s; }
; __device__ __forceinline__ f32x4 gelu4(f32x4 v) { f32x2 a = gelu_pk((f32x2){v[0], v[1]}), b = gelu_pk((f32x2){v[2], v[3]}); return (f32x4){a.x, a.y, b.x, b.y}; }
; __device__ __forceinline__ f32x2 gelu_pk(f32x2 v) {
;     const f32x2 av = __builtin_elementwise_abs(v), d = av * 0.2316418882f + 1.0f;
;     f32x2 t; t.x = __builtin_amdgcn_rcpf(d.x); t.y = __builtin_amdgcn_rcpf(d.y);
;     f32x2 q = t * 0.5307027145f + (-0.7265760135f); q = q * t + 0.7107068705f; q = q * t + (-0.142248368f); q = q * t + 0.127414796f; q = q * t;
;     const f32x2 s = (v * v) * (-0.72134752044f);
;     f32x2 e; e.x = __builtin_amdgcn_exp2f(s.x); e.y = __builtin_amdgcn_exp2f(s.y);
;     const f32x2 m = v * (q * e), r = v - m;
;     f32x2 o; o.x = v.x < 0.f ? m.x : r.x; o.y = v.y < 0.f ? m.y : r.y; return o;
; }
; template <int EK>
; __device__ __forceinline__ void epi_tile(const f32x4 (&acc)[2][2][4][2], const Unit& u, int wr, int wc, int fr, int fq, const EpiArgs& E, const LAS float* rt) {
;     ...
;             } else if (EK == EK_GELU) {
;                 const float r = rr[ai][m]; float ss = 0.f;
; #pragma unroll
;                 for (int bj = 0; bj < 2; ++bj) { const int col = u.pn * BM + bj * HALF + wc * 32 + fq * 8;
;                     const f32x4 z0 = gelu4(acc[ai][bj][m][0] * r), z1 = gelu4(acc[ai][bj][m][1] * r); ss += dot4(z0) + dot4(z1);
;                     const u32x2 lo = pack4(z0), hi = pack4(z1);
;                     *(u32x4*)(E.ob + (size_t)row * E.ldb + col) = (u32x4){lo.x, lo.y, hi.x, hi.y}; }
;                 if (u.pn >= 4) { ss = quad_sum(ss); if (fq == 0) E.stOut[(size_t)row * 16 + (u.pn - 4) * 4 + wc] = ss; }
	v_pk_mul_f32 v[172:173], v[182:183], v[172:173]
	v_rcp_f32_e32 v186, v186
	v_rcp_f32_e32 v187, v187
	v_pk_mul_f32 v[172:173], v[178:179], v[172:173]
	v_pk_mul_f32 v[182:183], v[174:175], v[174:175]
	v_pk_mul_f32 v[178:179], v[180:181], v[172:173]
	v_pk_fma_f32 v[172:173], v[180:181], v[172:173], v[180:181] neg_lo:[1,0,0] neg_hi:[1,0,0]
	s_nop 0
	v_cndmask_b32_e32 v172, v172, v178, vcc
	v_cmp_gt_f32_e32 vcc, 0, v181
	v_pk_mul_f32 v[180:181], v[182:183], s[58:59] op_sel_hi:[1,0]
	v_pk_mul_f32 v[182:183], v[66:67], v[176:177] op_sel_hi:[1,0]
	v_cndmask_b32_e32 v173, v173, v179, vcc
	v_pk_fma_f32 v[178:179], v[186:187], s[42:43], v[158:159] op_sel_hi:[1,0,0]
	v_exp_f32_e32 v180, v180
	v_pk_fma_f32 v[178:179], v[186:187], v[178:179], s[52:53] op_sel_hi:[1,1,0]
	v_exp_f32_e32 v181, v181
	v_pk_fma_f32 v[178:179], v[186:187], v[178:179], s[54:55] op_sel_hi:[1,1,0]
	v_cmp_gt_f32_e32 vcc, 0, v174
	v_pk_fma_f32 v[178:179], v[186:187], v[178:179], s[56:57] op_sel_hi:[1,1,0]
	s_nop 0
	v_pk_mul_f32 v[178:179], v[186:187], v[178:179]
	v_fma_f32 v186, |v182|, s40, 1.0
	v_fma_f32 v187, |v183|, s40, 1.0
	v_pk_mul_f32 v[178:179], v[180:181], v[178:179]
	v_rcp_f32_e32 v186, v186
	v_rcp_f32_e32 v187, v187
	v_pk_mul_f32 v[180:181], v[174:175], v[178:179]
	v_pk_fma_f32 v[178:179], v[174:175], v[178:179], v[174:175] neg_lo:[1,0,0] neg_hi:[1,0,0]
	s_nop 0
	v_cndmask_b32_e32 v174, v178, v180, vcc
	v_cmp_gt_f32_e32 vcc, 0, v175
	s_nop 1
	v_cndmask_b32_e32 v175, v179, v181, vcc
	v_pk_mul_f32 v[180:181], v[182:183], v[182:183]
	v_pk_mul_f32 v[178:179], v[68:69], v[176:177] op_sel_hi:[1,0]
	v_pk_fma_f32 v[176:177], v[186:187], s[42:43], v[158:159] op_sel_hi:[1,0,0]
	v_pk_mul_f32 v[180:181], v[180:181], s[58:59] op_sel_hi:[1,0]
	v_pk_fma_f32 v[176:177], v[186:187], v[176:177], s[52:53] op_sel_hi:[1,1,0]
	v_exp_f32_e32 v180, v180
	v_exp_f32_e32 v181, v181
	v_pk_fma_f32 v[176:177], v[186:187], v[176:177], s[54:55] op_sel_hi:[1,1,0]
	v_pk_fma_f32 v[176:177], v[186:187], v[176:177], s[56:57] op_sel_hi:[1,1,0]
	v_fma_f32 v188, |v178|, s40, 1.0
	v_fma_f32 v189, |v179|, s40, 1.0
	v_pk_mul_f32 v[176:177], v[186:187], v[176:177]
	v_rcp_f32_e32 v188, v188
	v_rcp_f32_e32 v189, v189
	v_pk_mul_f32 v[176:177], v[180:181], v[176:177]
	v_max_f32_e32 v180, 0, v182
	v_max_f32_e32 v181, 0, v183
	v_fma_f32 v176, -|v182|, v176, v180
	v_fma_f32 v177, -|v183|, v177, v181
	v_pk_mul_f32 v[186:187], v[178:179], v[178:179]
	v_pk_fma_f32 v[158:159], v[188:189], s[42:43], v[158:159] op_sel_hi:[1,0,0]
	v_cndmask_b32_e64 v182, 0, 1, s[78:79]
	v_pk_mul_f32 v[180:181], v[186:187], s[58:59] op_sel_hi:[1,0]
	v_pk_fma_f32 v[158:159], v[188:189], v[158:159], s[52:53] op_sel_hi:[1,1,0]
	v_exp_f32_e32 v180, v180
	v_exp_f32_e32 v181, v181
	v_pk_fma_f32 v[158:159], v[188:189], v[158:159], s[54:55] op_sel_hi:[1,1,0]
	v_pk_fma_f32 v[158:159], v[188:189], v[158:159], s[56:57] op_sel_hi:[1,1,0]
	v_cmp_ne_u32_e64 s[10:11], 1, v182
	v_pk_mul_f32 v[158:159], v[188:189], v[158:159]
	s_nop 0
	v_pk_mul_f32 v[158:159], v[180:181], v[158:159]
	s_nop 0
	v_max_f32_e32 v180, 0, v178
	v_max_f32_e32 v181, 0, v179
	v_fma_f32 v158, -|v178|, v158, v180
	v_fma_f32 v159, -|v179|, v159, v181
	v_cvt_pk_bf16_f32 v178, v172, v173
	s_nop 0
	v_cvt_pk_bf16_f32 v179, v174, v175
	v_cvt_pk_bf16_f32 v180, v176, v177
	s_nop 1
	s_andn2_b64 vcc, exec, s[78:79]
	v_cvt_pk_bf16_f32 v181, v158, v159
	global_store_dwordx4 v[184:185], v[178:181], off offset:256
	s_cbranch_vccnz .LBB0_940
	v_mul_f32_e32 v165, v165, v165
	v_fmac_f32_e32 v165, v151, v151
	v_mul_f32_e32 v151, v167, v167
	v_fmac_f32_e32 v151, v166, v166
	v_add_f32_e32 v151, v165, v151
	v_mul_f32_e32 v165, v169, v169
	v_mul_f32_e32 v166, v171, v171
	v_fmac_f32_e32 v165, v168, v168
	v_fmac_f32_e32 v166, v170, v170
	v_add_f32_e32 v165, v165, v166
	v_add_f32_e32 v151, v151, v165
	v_mul_f32_e32 v165, v173, v173
	v_mul_f32_e32 v166, v175, v175
	v_fmac_f32_e32 v165, v172, v172
	v_fmac_f32_e32 v166, v174, v174
	v_add_f32_e32 v165, v165, v166
	v_mul_f32_e32 v166, v177, v177
	v_mul_f32_e32 v159, v159, v159
	v_fmac_f32_e32 v166, v176, v176
	v_fmac_f32_e32 v159, v158, v158
	v_add_f32_e32 v158, v166, v159
	v_add_f32_e32 v158, v165, v158
	v_and_b32_e32 v159, 64, v164
	v_add_f32_e32 v151, v151, v158
	v_xor_b32_e32 v158, 16, v164
	v_add_u32_e32 v159, 64, v159
	v_cmp_lt_i32_e32 vcc, v158, v159
	s_nop 1
	v_cndmask_b32_e32 v158, v164, v158, vcc
	v_lshlrev_b32_e32 v158, 2, v158
	ds_bpermute_b32 v158, v158, v151
	s_waitcnt lgkmcnt(0)
	v_add_f32_e32 v151, v151, v158
	v_xor_b32_e32 v158, 32, v164
	v_cmp_lt_i32_e32 vcc, v158, v159
	s_nop 1
	v_cndmask_b32_e32 v158, v164, v158, vcc
	v_lshlrev_b32_e32 v158, 2, v158
	ds_bpermute_b32 v158, v158, v151
	s_and_saveexec_b64 s[78:79], s[4:5]
	s_cbranch_execz .LBB0_939
	v_lshlrev_b64 v[156:157], 6, v[156:157]
	v_lshl_add_u64 v[156:157], s[18:19], 0, v[156:157]
	v_lshl_add_u64 v[156:157], s[76:77], 2, v[156:157]
	s_lshl_b32 s14, s59, 2
	v_lshl_add_u64 v[156:157], v[156:157], 0, s[14:15]
	s_waitcnt lgkmcnt(0)
	v_add_f32_e32 v151, v151, v158
	global_store_dword v[156:157], v151, off

; __device__ __forceinline__ float dot4(f32x4 v) { return (v[0] * v[0] + v[1] * v[1]) + (v[2] * v[2] + v[3] * v[3]); }
; __device__ __forceinline__ u32x2 pack4(f32x4 v) { u32x2 w; w.x = cvt_pk_bf16(v[0], v[1]); w.y = cvt_pk_bf16(v[2], v[3]); return w; }
; __device__ __forceinline__ float quad_sum(float s) { s += __shfl_xor(s, 16); s += __shfl_xor(s, 32); return s; }
; __device__ __forceinline__ f32x4 gelu4(f32x4 v) { f32x2 a = gelu_pk((f32x2){v[0], v[1]}), b = gelu_pk((f32x2){v[2], v[3]}); return (f32x4){a.x, a.y, b.x, b.y}; }
; __device__ __forceinline__ f32x2 gelu_pk(f32x2 v) {
;     const f32x2 av = __builtin_elementwise_abs(v), d = av * 0.2316418882f + 1.0f;
;     f32x2 t; t.x = __builtin_amdgcn_rcpf(d.x); t.y = __builtin_amdgcn_rcpf(d.y);
;     f32x2 q = t * 0.5307027145f + (-0.7265760135f); q = q * t + 0.7107068705f; q = q * t + (-0.142248368f); q = q * t + 0.127414796f; q = q * t;
;     const f32x2 s = (v * v) * (-0.72134752044f);
;     f32x2 e; e.x = __builtin_amdgcn_exp2f(s.x); e.y = __builtin_amdgcn_exp2f(s.y);
;     const f32x2 m = v * (q * e), r = v - m;
;     f32x2 o; o.x = v.x < 0.f ? m.x : r.x; o.y = v.y < 0.f ? m.y : r.y; return o;
; }
; template <int EK>
; __device__ __forceinline__ void epi_tile(const f32x4 (&acc)[2][2][4][2], const Unit& u, int wr, int wc, int fr, int fq, const EpiArgs& E, const LAS float* rt) {
;     ...
;             } else if (EK == EK_GELU) {
;                 const float r = rr[ai][m]; float ss = 0.f;
; #pragma unroll
;                 for (int bj = 0; bj < 2; ++bj) { const int col = u.pn * BM + bj * HALF + wc * 32 + fq * 8;
;                     const f32x4 z0 = gelu4(acc[ai][bj][m][0] * r), z1 = gelu4(acc[ai][bj][m][1] * r); ss += dot4(z0) + dot4(z1);
;                     const u32x2 lo = pack4(z0), hi = pack4(z1);
;                     *(u32x4*)(E.ob + (size_t)row * E.ldb + col) = (u32x4){lo.x, lo.y, hi.x, hi.y}; }
;                 if (u.pn >= 4) { ss = quad_sum(ss); if (fq == 0) E.stOut[(size_t)row * 16 + (u.pn - 4) * 4 + wc] = ss; }
.LBB0_940:
	v_pk_mul_f32 v[166:167], v[94:95], v[154:155] op_sel_hi:[1,0]
	v_pk_mul_f32 v[170:171], v[96:97], v[154:155] op_sel_hi:[1,0]
	s_waitcnt lgkmcnt(0)
	v_fma_f32 v158, |v166|, s40, 1.0
	v_fma_f32 v159, |v167|, s40, 1.0
	v_pk_mul_f32 v[174:175], v[166:167], v[166:167]
	v_rcp_f32_e32 v168, v158
	v_rcp_f32_e32 v169, v159
	v_mov_b64_e32 v[158:159], s[44:45]
	v_pk_mul_f32 v[174:175], v[174:175], s[58:59] op_sel_hi:[1,0]
	v_pk_fma_f32 v[172:173], v[168:169], s[42:43], v[158:159] op_sel_hi:[1,0,0]
	v_exp_f32_e32 v174, v174
	v_pk_fma_f32 v[172:173], v[168:169], v[172:173], s[52:53] op_sel_hi:[1,1,0]
	v_exp_f32_e32 v175, v175
	v_pk_fma_f32 v[172:173], v[168:169], v[172:173], s[54:55] op_sel_hi:[1,1,0]
	v_pk_fma_f32 v[172:173], v[168:169], v[172:173], s[56:57] op_sel_hi:[1,1,0]
	v_fma_f32 v176, |v170|, s40, 1.0
	v_fma_f32 v177, |v171|, s40, 1.0
	v_pk_mul_f32 v[168:169], v[168:169], v[172:173]
	v_rcp_f32_e32 v176, v176
	v_rcp_f32_e32 v177, v177
	v_pk_mul_f32 v[168:169], v[174:175], v[168:169]
	v_max_f32_e32 v174, 0, v166
	v_max_f32_e32 v175, 0, v167
	v_fma_f32 v151, -|v166|, v168, v174
	v_fma_f32 v165, -|v167|, v169, v175
	v_pk_mul_f32 v[172:173], v[170:171], v[170:171]
	v_pk_fma_f32 v[166:167], v[176:177], s[42:43], v[158:159] op_sel_hi:[1,0,0]
	v_or_b32_e32 v156, 32, v150
	v_pk_mul_f32 v[168:169], v[172:173], s[58:59] op_sel_hi:[1,0]
	v_pk_fma_f32 v[166:167], v[176:177], v[166:167], s[52:53] op_sel_hi:[1,1,0]
	v_exp_f32_e32 v168, v168
	v_exp_f32_e32 v169, v169
	v_pk_mul_f32 v[172:173], v[90:91], v[154:155] op_sel_hi:[1,0]
	v_pk_fma_f32 v[166:167], v[176:177], v[166:167], s[54:55] op_sel_hi:[1,1,0]
	v_pk_fma_f32 v[166:167], v[176:177], v[166:167], s[56:57] op_sel_hi:[1,1,0]
	v_fma_f32 v174, |v172|, s40, 1.0
	v_fma_f32 v175, |v173|, s40, 1.0
	v_pk_mul_f32 v[166:167], v[176:177], v[166:167]
	v_rcp_f32_e32 v174, v174
	v_rcp_f32_e32 v175, v175
	v_pk_mul_f32 v[166:167], v[168:169], v[166:167]
	v_max_f32_e32 v168, 0, v170
	v_max_f32_e32 v169, 0, v171
	v_fma_f32 v166, -|v170|, v166, v168
	v_fma_f32 v167, -|v171|, v167, v169
	v_pk_mul_f32 v[176:177], v[172:173], v[172:173]
	v_pk_mul_f32 v[170:171], v[92:93], v[154:155] op_sel_hi:[1,0]
	v_pk_mul_f32 v[176:177], v[176:177], s[58:59] op_sel_hi:[1,0]
	v_pk_fma_f32 v[168:169], v[174:175], s[42:43], v[158:159] op_sel_hi:[1,0,0]
	v_exp_f32_e32 v176, v176
	v_pk_fma_f32 v[168:169], v[174:175], v[168:169], s[52:53] op_sel_hi:[1,1,0]
	v_exp_f32_e32 v177, v177
	v_pk_fma_f32 v[168:169], v[174:175], v[168:169], s[54:55] op_sel_hi:[1,1,0]
	v_fma_f32 v178, |v170|, s40, 1.0
	v_fma_f32 v179, |v171|, s40, 1.0
	v_pk_fma_f32 v[168:169], v[174:175], v[168:169], s[56:57] op_sel_hi:[1,1,0]
	v_rcp_f32_e32 v178, v178
	v_rcp_f32_e32 v179, v179
	v_pk_mul_f32 v[168:169], v[174:175], v[168:169]
	v_pk_mul_f32 v[168:169], v[176:177], v[168:169]
	v_pk_mul_f32 v[174:175], v[170:171], v[170:171]
	v_max_f32_e32 v176, 0, v172
	v_max_f32_e32 v177, 0, v173
	v_fma_f32 v168, -|v172|, v168, v176
	v_fma_f32 v169, -|v173|, v169, v177
	v_pk_mul_f32 v[174:175], v[174:175], s[58:59] op_sel_hi:[1,0]
	v_pk_fma_f32 v[172:173], v[178:179], s[42:43], v[158:159] op_sel_hi:[1,0,0]
	v_exp_f32_e32 v174, v174
	v_pk_fma_f32 v[172:173], v[178:179], v[172:173], s[52:53] op_sel_hi:[1,1,0]
	v_exp_f32_e32 v175, v175
	v_pk_fma_f32 v[172:173], v[178:179], v[172:173], s[54:55] op_sel_hi:[1,1,0]
	v_ashrrev_i32_e32 v157, 31, v156
	v_pk_fma_f32 v[172:173], v[178:179], v[172:173], s[56:57] op_sel_hi:[1,1,0]
	v_pk_mul_f32 v[172:173], v[178:179], v[172:173]
	v_pk_mul_f32 v[178:179], v[62:63], v[154:155] op_sel_hi:[1,0]
	v_pk_mul_f32 v[172:173], v[174:175], v[172:173]
	v_fma_f32 v180, |v178|, s40, 1.0
	v_fma_f32 v181, |v179|, s40, 1.0
	v_pk_mul_f32 v[174:175], v[170:171], v[172:173]
	v_rcp_f32_e32 v180, v180
	v_rcp_f32_e32 v181, v181
	v_pk_fma_f32 v[172:173], v[170:171], v[172:173], v[170:171] neg_lo:[1,0,0] neg_hi:[1,0,0]
	v_cmp_gt_f32_e32 vcc, 0, v170
	v_lshlrev_b64 v[176:177], 12, v[156:157]
	v_lshl_add_u64 v[176:177], s[64:65], 0, v[176:177]
	v_cndmask_b32_e32 v170, v172, v174, vcc
	v_cmp_gt_f32_e32 vcc, 0, v171
	v_cvt_pk_bf16_f32 v172, v151, v165
	v_lshl_add_u64 v[182:183], v[146:147], 1, v[176:177]
	v_pk_mul_f32 v[176:177], v[178:179], v[178:179]
	v_cndmask_b32_e32 v171, v173, v175, vcc
	v_cvt_pk_bf16_f32 v173, v166, v167
	v_cvt_pk_bf16_f32 v174, v168, v169
	v_cvt_pk_bf16_f32 v175, v170, v171
	global_store_dwordx4 v[182:183], v[172:175], off
	v_pk_mul_f32 v[176:177], v[176:177], s[58:59] op_sel_hi:[1,0]
	v_cmp_gt_f32_e32 vcc, 0, v178
	v_pk_fma_f32 v[172:173], v[180:181], s[42:43], v[158:159] op_sel_hi:[1,0,0]
	v_pk_mul_f32 v[174:175], v[64:65], v[154:155] op_sel_hi:[1,0]
	v_pk_fma_f32 v[172:173], v[180:181], v[172:173], s[52:53] op_sel_hi:[1,1,0]
	v_exp_f32_e32 v176, v176
	v_exp_f32_e32 v177, v177
	v_pk_fma_f32 v[172:173], v[180:181], v[172:173], s[54:55] op_sel_hi:[1,1,0]
	v_pk_fma_f32 v[172:173], v[180:181], v[172:173], s[56:57] op_sel_hi:[1,1,0]
	v_fma_f32 v184, |v174|, s40, 1.0
; __device__ __forceinline__ float dot4(f32x4 v) { return (v[0] * v[0] + v[1] * v[1]) + (v[2] * v[2] + v[3] * v[3]); }
; __device__ __forceinline__ u32x2 pack4(f32x4 v) { u32x2 w; w.x = cvt_pk_bf16(v[0], v[1]); w.y = cvt_pk_bf16(v[2], v[3]); return w; }
; __device__ __forceinline__ float quad_sum(float s) { s += __shfl_xor(s, 16); s += __shfl_xor(s, 32); return s; }
; __device__ __forceinline__ f32x4 gelu4(f32x4 v) { f32x2 a = gelu_pk((f32x2){v[0], v[1]}), b = gelu_pk((f32x2){v[2], v[3]}); return (f32x4){a.x, a.y, b.x, b.y}; }
; __device__ __forceinline__ f32x2 gelu_pk(f32x2 v) {
;     const f32x2 av = __builtin_elementwise_abs(v), d = av * 0.2316418882f + 1.0f;
;     f32x2 t; t.x = __builtin_amdgcn_rcpf(d.x); t.y = __builtin_amdgcn_rcpf(d.y);
;     f32x2 q = t * 0.5307027145f + (-0.7265760135f); q = q * t + 0.7107068705f; q = q * t + (-0.142248368f); q = q * t + 0.127414796f; q = q * t;
;     const f32x2 s = (v * v) * (-0.72134752044f);
;     f32x2 e; e.x = __builtin_amdgcn_exp2f(s.x); e.y = __builtin_amdgcn_exp2f(s.y);
;     const f32x2 m = v * (q * e), r = v - m;
;     f32x2 o; o.x = v.x < 0.f ? m.x : r.x; o.y = v.y < 0.f ? m.y : r.y; return o;
; }
; template <int EK>
; __device__ __forceinline__ void epi_tile(const f32x4 (&acc)[2][2][4][2], const Unit& u, int wr, int wc, int fr, int fq, const EpiArgs& E, const LAS float* rt) {
;     ...
;             } else if (EK == EK_GELU) {
;                 const float r = rr[ai][m]; float ss = 0.f;
; #pragma unroll
;                 for (int bj = 0; bj < 2; ++bj) { const int col = u.pn * BM + bj * HALF + wc * 32 + fq * 8;
;                     const f32x4 z0 = gelu4(acc[ai][bj][m][0] * r), z1 = gelu4(acc[ai][bj][m][1] * r); ss += dot4(z0) + dot4(z1);
;                     const u32x2 lo = pack4(z0), hi = pack4(z1);
;                     *(u32x4*)(E.ob + (size_t)row * E.ldb + col) = (u32x4){lo.x, lo.y, hi.x, hi.y}; }
;                 if (u.pn >= 4) { ss = quad_sum(ss); if (fq == 0) E.stOut[(size_t)row * 16 + (u.pn - 4) * 4 + wc] = ss; }
	v_fma_f32 v185, |v175|, s40, 1.0
	v_pk_mul_f32 v[172:173], v[180:181], v[172:173]
	v_rcp_f32_e32 v184, v184
	v_rcp_f32_e32 v185, v185
	v_pk_mul_f32 v[172:173], v[176:177], v[172:173]
	v_pk_mul_f32 v[180:181], v[174:175], v[174:175]
	v_pk_mul_f32 v[176:177], v[178:179], v[172:173]
	v_pk_fma_f32 v[172:173], v[178:179], v[172:173], v[178:179] neg_lo:[1,0,0] neg_hi:[1,0,0]
	s_nop 0
	v_cndmask_b32_e32 v172, v172, v176, vcc
	v_cmp_gt_f32_e32 vcc, 0, v179
	v_pk_mul_f32 v[178:179], v[180:181], s[58:59] op_sel_hi:[1,0]
	v_pk_mul_f32 v[180:181], v[58:59], v[154:155] op_sel_hi:[1,0]
	v_cndmask_b32_e32 v173, v173, v177, vcc
	v_pk_fma_f32 v[176:177], v[184:185], s[42:43], v[158:159] op_sel_hi:[1,0,0]
	v_exp_f32_e32 v178, v178
	v_pk_fma_f32 v[176:177], v[184:185], v[176:177], s[52:53] op_sel_hi:[1,1,0]
	v_exp_f32_e32 v179, v179
	v_pk_fma_f32 v[176:177], v[184:185], v[176:177], s[54:55] op_sel_hi:[1,1,0]
	v_cmp_gt_f32_e32 vcc, 0, v174
	v_pk_fma_f32 v[176:177], v[184:185], v[176:177], s[56:57] op_sel_hi:[1,1,0]
	v_pk_mul_f32 v[186:187], v[180:181], v[180:181]
	v_pk_mul_f32 v[176:177], v[184:185], v[176:177]
	v_fma_f32 v184, |v180|, s40, 1.0
	v_fma_f32 v185, |v181|, s40, 1.0
	v_pk_mul_f32 v[176:177], v[178:179], v[176:177]
	v_rcp_f32_e32 v184, v184
	v_rcp_f32_e32 v185, v185
	v_pk_mul_f32 v[178:179], v[174:175], v[176:177]
	v_pk_fma_f32 v[176:177], v[174:175], v[176:177], v[174:175] neg_lo:[1,0,0] neg_hi:[1,0,0]
	v_pk_mul_f32 v[186:187], v[186:187], s[58:59] op_sel_hi:[1,0]
	v_cndmask_b32_e32 v174, v176, v178, vcc
	v_cmp_gt_f32_e32 vcc, 0, v175
	v_exp_f32_e32 v186, v186
	v_exp_f32_e32 v187, v187
	v_cndmask_b32_e32 v175, v177, v179, vcc
	v_pk_mul_f32 v[178:179], v[60:61], v[154:155] op_sel_hi:[1,0]
	v_pk_fma_f32 v[176:177], v[184:185], s[42:43], v[158:159] op_sel_hi:[1,0,0]
	v_pk_fma_f32 v[176:177], v[184:185], v[176:177], s[52:53] op_sel_hi:[1,1,0]
	v_pk_fma_f32 v[176:177], v[184:185], v[176:177], s[54:55] op_sel_hi:[1,1,0]
	v_fma_f32 v188, |v178|, s40, 1.0
	v_fma_f32 v189, |v179|, s40, 1.0
	v_pk_fma_f32 v[176:177], v[184:185], v[176:177], s[56:57] op_sel_hi:[1,1,0]
	v_rcp_f32_e32 v188, v188
	v_rcp_f32_e32 v189, v189
	v_pk_mul_f32 v[176:177], v[184:185], v[176:177]
	v_pk_mul_f32 v[184:185], v[178:179], v[178:179]
	v_pk_mul_f32 v[176:177], v[186:187], v[176:177]
	v_max_f32_e32 v186, 0, v180
	v_max_f32_e32 v187, 0, v181
	v_fma_f32 v154, -|v180|, v176, v186
	v_fma_f32 v176, -|v181|, v177, v187
	v_pk_fma_f32 v[158:159], v[188:189], s[42:43], v[158:159] op_sel_hi:[1,0,0]
	v_pk_mul_f32 v[180:181], v[184:185], s[58:59] op_sel_hi:[1,0]
	v_pk_fma_f32 v[158:159], v[188:189], v[158:159], s[52:53] op_sel_hi:[1,1,0]
	v_exp_f32_e32 v180, v180
	v_exp_f32_e32 v181, v181
	v_pk_fma_f32 v[158:159], v[188:189], v[158:159], s[54:55] op_sel_hi:[1,1,0]
	v_pk_fma_f32 v[158:159], v[188:189], v[158:159], s[56:57] op_sel_hi:[1,1,0]
	v_pk_mul_f32 v[158:159], v[188:189], v[158:159]
	s_nop 0
	v_pk_mul_f32 v[158:159], v[180:181], v[158:159]
	s_nop 0
	v_max_f32_e32 v180, 0, v178
	v_max_f32_e32 v181, 0, v179
	v_fma_f32 v158, -|v178|, v158, v180
	v_fma_f32 v159, -|v179|, v159, v181
	v_cvt_pk_bf16_f32 v178, v172, v173
	s_nop 0
	v_cvt_pk_bf16_f32 v179, v174, v175
	v_cvt_pk_bf16_f32 v180, v154, v176
	s_nop 1
	s_and_b64 vcc, exec, s[10:11]
	v_cvt_pk_bf16_f32 v181, v158, v159
	global_store_dwordx4 v[182:183], v[178:181], off offset:256
	s_cbranch_vccnz .LBB0_944
	v_mul_f32_e32 v165, v165, v165
	v_fmac_f32_e32 v165, v151, v151
	v_mul_f32_e32 v151, v167, v167
	v_fmac_f32_e32 v151, v166, v166
	v_add_f32_e32 v151, v165, v151
	v_mul_f32_e32 v165, v169, v169
	v_mul_f32_e32 v166, v171, v171
	v_fmac_f32_e32 v165, v168, v168
	v_fmac_f32_e32 v166, v170, v170
	v_add_f32_e32 v165, v165, v166
	v_add_f32_e32 v151, v151, v165
	v_mul_f32_e32 v165, v173, v173
	v_mul_f32_e32 v166, v175, v175
	v_fmac_f32_e32 v165, v172, v172
	v_fmac_f32_e32 v166, v174, v174
	v_add_f32_e32 v165, v165, v166
	v_mul_f32_e32 v166, v176, v176
	v_fmac_f32_e32 v166, v154, v154
	v_mul_f32_e32 v154, v159, v159
	v_fmac_f32_e32 v154, v158, v158
	v_add_f32_e32 v154, v166, v154
	v_add_f32_e32 v154, v165, v154
	v_and_b32_e32 v158, 64, v164
	v_add_f32_e32 v151, v151, v154
	v_xor_b32_e32 v154, 16, v164
	v_add_u32_e32 v158, 64, v158
	v_cmp_lt_i32_e32 vcc, v154, v158
	s_nop 1
	v_cndmask_b32_e32 v154, v164, v154, vcc
	v_lshlrev_b32_e32 v154, 2, v154
	ds_bpermute_b32 v154, v154, v151
	s_waitcnt lgkmcnt(0)
	v_add_f32_e32 v151, v151, v154
	v_xor_b32_e32 v154, 32, v164
	v_cmp_lt_i32_e32 vcc, v154, v158
	s_nop 1
	v_cndmask_b32_e32 v154, v164, v154, vcc
	v_lshlrev_b32_e32 v154, 2, v154
	ds_bpermute_b32 v154, v154, v151
	s_and_saveexec_b64 s[78:79], s[4:5]
	s_cbranch_execz .LBB0_943
	v_lshlrev_b64 v[156:157], 6, v[156:157]
	v_lshl_add_u64 v[156:157], s[18:19], 0, v[156:157]
	v_lshl_add_u64 v[156:157], s[76:77], 2, v[156:157]
	s_lshl_b32 s14, s59, 2
	v_lshl_add_u64 v[156:157], v[156:157], 0, s[14:15]
	s_waitcnt lgkmcnt(0)
	v_add_f32_e32 v151, v151, v154
	global_store_dword v[156:157], v151, off

; __device__ __forceinline__ float dot4(f32x4 v) { return (v[0] * v[0] + v[1] * v[1]) + (v[2] * v[2] + v[3] * v[3]); }
; __device__ __forceinline__ u32x2 pack4(f32x4 v) { u32x2 w; w.x = cvt_pk_bf16(v[0], v[1]); w.y = cvt_pk_bf16(v[2], v[3]); return w; }
; __device__ __forceinline__ float quad_sum(float s) { s += __shfl_xor(s, 16); s += __shfl_xor(s, 32); return s; }
; __device__ __forceinline__ f32x4 gelu4(f32x4 v) { f32x2 a = gelu_pk((f32x2){v[0], v[1]}), b = gelu_pk((f32x2){v[2], v[3]}); return (f32x4){a.x, a.y, b.x, b.y}; }
; __device__ __forceinline__ f32x2 gelu_pk(f32x2 v) {
;     const f32x2 av = __builtin_elementwise_abs(v), d = av * 0.2316418882f + 1.0f;
;     f32x2 t; t.x = __builtin_amdgcn_rcpf(d.x); t.y = __builtin_amdgcn_rcpf(d.y);
;     f32x2 q = t * 0.5307027145f + (-0.7265760135f); q = q * t + 0.7107068705f; q = q * t + (-0.142248368f); q = q * t + 0.127414796f; q = q * t;
;     const f32x2 s = (v * v) * (-0.72134752044f);
;     f32x2 e; e.x = __builtin_amdgcn_exp2f(s.x); e.y = __builtin_amdgcn_exp2f(s.y);
;     const f32x2 m = v * (q * e), r = v - m;
;     f32x2 o; o.x = v.x < 0.f ? m.x : r.x; o.y = v.y < 0.f ? m.y : r.y; return o;
; }
; template <int EK>
; __device__ __forceinline__ void epi_tile(const f32x4 (&acc)[2][2][4][2], const Unit& u, int wr, int wc, int fr, int fq, const EpiArgs& E, const LAS float* rt) {
;     ...
;             } else if (EK == EK_GELU) {
;                 const float r = rr[ai][m]; float ss = 0.f;
; #pragma unroll
;                 for (int bj = 0; bj < 2; ++bj) { const int col = u.pn * BM + bj * HALF + wc * 32 + fq * 8;
;                     const f32x4 z0 = gelu4(acc[ai][bj][m][0] * r), z1 = gelu4(acc[ai][bj][m][1] * r); ss += dot4(z0) + dot4(z1);
;                     const u32x2 lo = pack4(z0), hi = pack4(z1);
;                     *(u32x4*)(E.ob + (size_t)row * E.ldb + col) = (u32x4){lo.x, lo.y, hi.x, hi.y}; }
;                 if (u.pn >= 4) { ss = quad_sum(ss); if (fq == 0) E.stOut[(size_t)row * 16 + (u.pn - 4) * 4 + wc] = ss; }
.LBB0_944:
	v_mov_b32_e32 v174, v155
	v_pk_mul_f32 v[158:159], v[86:87], v[174:175] op_sel_hi:[1,0]
	v_pk_mul_f32 v[168:169], v[88:89], v[174:175] op_sel_hi:[1,0]
	v_fma_f32 v156, |v158|, s40, 1.0
	v_fma_f32 v157, |v159|, s40, 1.0
	v_pk_mul_f32 v[172:173], v[158:159], v[158:159]
	v_rcp_f32_e32 v166, v156
	v_rcp_f32_e32 v167, v157
	v_mov_b64_e32 v[156:157], s[44:45]
	v_pk_mul_f32 v[172:173], v[172:173], s[58:59] op_sel_hi:[1,0]
	v_pk_fma_f32 v[170:171], v[166:167], s[42:43], v[156:157] op_sel_hi:[1,0,0]
	v_exp_f32_e32 v172, v172
	v_pk_fma_f32 v[170:171], v[166:167], v[170:171], s[52:53] op_sel_hi:[1,1,0]
	v_exp_f32_e32 v173, v173
	v_pk_fma_f32 v[170:171], v[166:167], v[170:171], s[54:55] op_sel_hi:[1,1,0]
	v_pk_fma_f32 v[170:171], v[166:167], v[170:171], s[56:57] op_sel_hi:[1,1,0]
	v_fma_f32 v176, |v168|, s40, 1.0
	v_fma_f32 v177, |v169|, s40, 1.0
	v_pk_mul_f32 v[166:167], v[166:167], v[170:171]
	v_rcp_f32_e32 v176, v176
	v_rcp_f32_e32 v177, v177
	v_pk_mul_f32 v[166:167], v[172:173], v[166:167]
	v_max_f32_e32 v172, 0, v158
	v_max_f32_e32 v173, 0, v159
	v_fma_f32 v151, -|v158|, v166, v172
	v_fma_f32 v158, -|v159|, v167, v173
	v_pk_mul_f32 v[170:171], v[168:169], v[168:169]
	v_pk_mul_f32 v[170:171], v[170:171], s[58:59] op_sel_hi:[1,0]
	s_waitcnt lgkmcnt(0)
	v_or_b32_e32 v154, 48, v150
	v_pk_fma_f32 v[166:167], v[176:177], s[42:43], v[156:157] op_sel_hi:[1,0,0]
	v_exp_f32_e32 v170, v170
	v_pk_fma_f32 v[166:167], v[176:177], v[166:167], s[52:53] op_sel_hi:[1,1,0]
	v_exp_f32_e32 v171, v171
	v_pk_fma_f32 v[166:167], v[176:177], v[166:167], s[54:55] op_sel_hi:[1,1,0]
	v_pk_mul_f32 v[172:173], v[82:83], v[174:175] op_sel_hi:[1,0]
	v_pk_fma_f32 v[166:167], v[176:177], v[166:167], s[56:57] op_sel_hi:[1,1,0]
	v_pk_mul_f32 v[166:167], v[176:177], v[166:167]
	v_fma_f32 v176, |v172|, s40, 1.0
	v_fma_f32 v177, |v173|, s40, 1.0
	v_pk_mul_f32 v[166:167], v[170:171], v[166:167]
	v_rcp_f32_e32 v176, v176
	v_rcp_f32_e32 v177, v177
	v_max_f32_e32 v170, 0, v168
	v_max_f32_e32 v171, 0, v169
	v_fma_f32 v159, -|v168|, v166, v170
	v_fma_f32 v165, -|v169|, v167, v171
	v_ashrrev_i32_e32 v155, 31, v154
	v_pk_mul_f32 v[168:169], v[84:85], v[174:175] op_sel_hi:[1,0]
	s_nop 0
	v_pk_mul_f32 v[170:171], v[172:173], v[172:173]
	v_pk_fma_f32 v[166:167], v[176:177], s[42:43], v[156:157] op_sel_hi:[1,0,0]
	v_pk_mul_f32 v[170:171], v[170:171], s[58:59] op_sel_hi:[1,0]
	v_pk_fma_f32 v[166:167], v[176:177], v[166:167], s[52:53] op_sel_hi:[1,1,0]
	v_exp_f32_e32 v170, v170
	v_exp_f32_e32 v171, v171
	v_pk_fma_f32 v[166:167], v[176:177], v[166:167], s[54:55] op_sel_hi:[1,1,0]
	v_pk_fma_f32 v[166:167], v[176:177], v[166:167], s[56:57] op_sel_hi:[1,1,0]
	v_fma_f32 v178, |v168|, s40, 1.0
	v_fma_f32 v179, |v169|, s40, 1.0
	v_pk_mul_f32 v[166:167], v[176:177], v[166:167]
	v_rcp_f32_e32 v178, v178
	v_rcp_f32_e32 v179, v179
	v_pk_mul_f32 v[166:167], v[170:171], v[166:167]
	v_max_f32_e32 v170, 0, v172
	v_max_f32_e32 v171, 0, v173
	v_fma_f32 v166, -|v172|, v166, v170
	v_fma_f32 v167, -|v173|, v167, v171
	v_pk_mul_f32 v[176:177], v[168:169], v[168:169]
	v_pk_mul_f32 v[172:173], v[176:177], s[58:59] op_sel_hi:[1,0]
	v_lshlrev_b64 v[176:177], 12, v[154:155]
	v_pk_fma_f32 v[170:171], v[178:179], s[42:43], v[156:157] op_sel_hi:[1,0,0]
	v_exp_f32_e32 v172, v172
	v_pk_fma_f32 v[170:171], v[178:179], v[170:171], s[52:53] op_sel_hi:[1,1,0]
	v_exp_f32_e32 v173, v173
	v_pk_fma_f32 v[170:171], v[178:179], v[170:171], s[54:55] op_sel_hi:[1,1,0]
	v_cmp_gt_f32_e32 vcc, 0, v168
	v_pk_fma_f32 v[170:171], v[178:179], v[170:171], s[56:57] op_sel_hi:[1,1,0]
	v_lshl_add_u64 v[176:177], s[64:65], 0, v[176:177]
	v_pk_mul_f32 v[170:171], v[178:179], v[170:171]
	v_pk_mul_f32 v[178:179], v[54:55], v[174:175] op_sel_hi:[1,0]
	v_pk_mul_f32 v[170:171], v[172:173], v[170:171]
	v_fma_f32 v180, |v178|, s40, 1.0
	v_fma_f32 v181, |v179|, s40, 1.0
	v_pk_mul_f32 v[172:173], v[168:169], v[170:171]
	v_rcp_f32_e32 v180, v180
	v_rcp_f32_e32 v181, v181
	v_pk_fma_f32 v[170:171], v[168:169], v[170:171], v[168:169] neg_lo:[1,0,0] neg_hi:[1,0,0]
	v_lshl_add_u64 v[182:183], v[146:147], 1, v[176:177]
	v_cndmask_b32_e32 v168, v170, v172, vcc
	v_cmp_gt_f32_e32 vcc, 0, v169
	v_cvt_pk_bf16_f32 v170, v151, v158
	v_pk_mul_f32 v[176:177], v[178:179], v[178:179]
	v_cvt_pk_bf16_f32 v172, v166, v167
	s_nop 0
	v_cndmask_b32_e32 v169, v171, v173, vcc
	v_cvt_pk_bf16_f32 v171, v159, v165
	v_cvt_pk_bf16_f32 v173, v168, v169
	global_store_dwordx4 v[182:183], v[170:173], off
	v_pk_mul_f32 v[176:177], v[176:177], s[58:59] op_sel_hi:[1,0]
	v_cmp_gt_f32_e32 vcc, 0, v178
	v_pk_fma_f32 v[170:171], v[180:181], s[42:43], v[156:157] op_sel_hi:[1,0,0]
	v_pk_mul_f32 v[172:173], v[56:57], v[174:175] op_sel_hi:[1,0]
	v_pk_fma_f32 v[170:171], v[180:181], v[170:171], s[52:53] op_sel_hi:[1,1,0]
	v_exp_f32_e32 v176, v176
	v_exp_f32_e32 v177, v177
	v_pk_fma_f32 v[170:171], v[180:181], v[170:171], s[54:55] op_sel_hi:[1,1,0]
	v_pk_fma_f32 v[170:171], v[180:181], v[170:171], s[56:57] op_sel_hi:[1,1,0]
	v_fma_f32 v184, |v172|, s40, 1.0
; __device__ __forceinline__ float dot4(f32x4 v) { return (v[0] * v[0] + v[1] * v[1]) + (v[2] * v[2] + v[3] * v[3]); }
; __device__ __forceinline__ u32x2 pack4(f32x4 v) { u32x2 w; w.x = cvt_pk_bf16(v[0], v[1]); w.y = cvt_pk_bf16(v[2], v[3]); return w; }
; __device__ __forceinline__ float quad_sum(float s) { s += __shfl_xor(s, 16); s += __shfl_xor(s, 32); return s; }
; __device__ __forceinline__ f32x4 gelu4(f32x4 v) { f32x2 a = gelu_pk((f32x2){v[0], v[1]}), b = gelu_pk((f32x2){v[2], v[3]}); return (f32x4){a.x, a.y, b.x, b.y}; }
; __device__ __forceinline__ f32x2 gelu_pk(f32x2 v) {
;     const f32x2 av = __builtin_elementwise_abs(v), d = av * 0.2316418882f + 1.0f;
;     f32x2 t; t.x = __builtin_amdgcn_rcpf(d.x); t.y = __builtin_amdgcn_rcpf(d.y);
;     f32x2 q = t * 0.5307027145f + (-0.7265760135f); q = q * t + 0.7107068705f; q = q * t + (-0.142248368f); q = q * t + 0.127414796f; q = q * t;
;     const f32x2 s = (v * v) * (-0.72134752044f);
;     f32x2 e; e.x = __builtin_amdgcn_exp2f(s.x); e.y = __builtin_amdgcn_exp2f(s.y);
;     const f32x2 m = v * (q * e), r = v - m;
;     f32x2 o; o.x = v.x < 0.f ? m.x : r.x; o.y = v.y < 0.f ? m.y : r.y; return o;
; }
; template <int EK>
; __device__ __forceinline__ void epi_tile(const f32x4 (&acc)[2][2][4][2], const Unit& u, int wr, int wc, int fr, int fq, const EpiArgs& E, const LAS float* rt) {
;     ...
;             } else if (EK == EK_GELU) {
;                 const float r = rr[ai][m]; float ss = 0.f;
; #pragma unroll
;                 for (int bj = 0; bj < 2; ++bj) { const int col = u.pn * BM + bj * HALF + wc * 32 + fq * 8;
;                     const f32x4 z0 = gelu4(acc[ai][bj][m][0] * r), z1 = gelu4(acc[ai][bj][m][1] * r); ss += dot4(z0) + dot4(z1);
;                     const u32x2 lo = pack4(z0), hi = pack4(z1);
;                     *(u32x4*)(E.ob + (size_t)row * E.ldb + col) = (u32x4){lo.x, lo.y, hi.x, hi.y}; }
;                 if (u.pn >= 4) { ss = quad_sum(ss); if (fq == 0) E.stOut[(size_t)row * 16 + (u.pn - 4) * 4 + wc] = ss; }
	v_fma_f32 v185, |v173|, s40, 1.0
	v_pk_mul_f32 v[170:171], v[180:181], v[170:171]
	v_rcp_f32_e32 v184, v184
	v_rcp_f32_e32 v185, v185
	v_pk_mul_f32 v[170:171], v[176:177], v[170:171]
	v_pk_mul_f32 v[180:181], v[172:173], v[172:173]
	v_pk_mul_f32 v[176:177], v[178:179], v[170:171]
	v_pk_fma_f32 v[170:171], v[178:179], v[170:171], v[178:179] neg_lo:[1,0,0] neg_hi:[1,0,0]
	s_nop 0
	v_cndmask_b32_e32 v170, v170, v176, vcc
	v_cmp_gt_f32_e32 vcc, 0, v179
	v_pk_mul_f32 v[178:179], v[180:181], s[58:59] op_sel_hi:[1,0]
	v_pk_mul_f32 v[180:181], v[50:51], v[174:175] op_sel_hi:[1,0]
	v_cndmask_b32_e32 v171, v171, v177, vcc
	v_pk_fma_f32 v[176:177], v[184:185], s[42:43], v[156:157] op_sel_hi:[1,0,0]
	v_exp_f32_e32 v178, v178
	v_pk_fma_f32 v[176:177], v[184:185], v[176:177], s[52:53] op_sel_hi:[1,1,0]
	v_exp_f32_e32 v179, v179
	v_pk_fma_f32 v[176:177], v[184:185], v[176:177], s[54:55] op_sel_hi:[1,1,0]
	v_cmp_gt_f32_e32 vcc, 0, v172
	v_pk_fma_f32 v[176:177], v[184:185], v[176:177], s[56:57] op_sel_hi:[1,1,0]
	s_nop 0
	v_pk_mul_f32 v[176:177], v[184:185], v[176:177]
	v_fma_f32 v184, |v180|, s40, 1.0
	v_fma_f32 v185, |v181|, s40, 1.0
	v_pk_mul_f32 v[176:177], v[178:179], v[176:177]
	v_rcp_f32_e32 v184, v184
	v_rcp_f32_e32 v185, v185
	v_pk_mul_f32 v[178:179], v[172:173], v[176:177]
	v_pk_fma_f32 v[176:177], v[172:173], v[176:177], v[172:173] neg_lo:[1,0,0] neg_hi:[1,0,0]
	s_nop 0
	v_cndmask_b32_e32 v172, v176, v178, vcc
	v_cmp_gt_f32_e32 vcc, 0, v173
	s_nop 1
	v_cndmask_b32_e32 v173, v177, v179, vcc
	v_pk_mul_f32 v[178:179], v[180:181], v[180:181]
	v_pk_mul_f32 v[176:177], v[52:53], v[174:175] op_sel_hi:[1,0]
	v_pk_fma_f32 v[174:175], v[184:185], s[42:43], v[156:157] op_sel_hi:[1,0,0]
	v_pk_mul_f32 v[178:179], v[178:179], s[58:59] op_sel_hi:[1,0]
	v_pk_fma_f32 v[174:175], v[184:185], v[174:175], s[52:53] op_sel_hi:[1,1,0]
	v_exp_f32_e32 v178, v178
	v_exp_f32_e32 v179, v179
	v_pk_fma_f32 v[174:175], v[184:185], v[174:175], s[54:55] op_sel_hi:[1,1,0]
	v_pk_fma_f32 v[174:175], v[184:185], v[174:175], s[56:57] op_sel_hi:[1,1,0]
	v_fma_f32 v186, |v176|, s40, 1.0
	v_fma_f32 v187, |v177|, s40, 1.0
	v_pk_mul_f32 v[174:175], v[184:185], v[174:175]
	v_rcp_f32_e32 v186, v186
	v_rcp_f32_e32 v187, v187
	v_pk_mul_f32 v[174:175], v[178:179], v[174:175]
	v_max_f32_e32 v178, 0, v180
	v_max_f32_e32 v179, 0, v181
	v_fma_f32 v174, -|v180|, v174, v178
	v_fma_f32 v175, -|v181|, v175, v179
	v_pk_mul_f32 v[184:185], v[176:177], v[176:177]
	v_pk_fma_f32 v[156:157], v[186:187], s[42:43], v[156:157] op_sel_hi:[1,0,0]
	s_nop 0
	v_pk_mul_f32 v[178:179], v[184:185], s[58:59] op_sel_hi:[1,0]
	v_pk_fma_f32 v[156:157], v[186:187], v[156:157], s[52:53] op_sel_hi:[1,1,0]
	v_exp_f32_e32 v178, v178
	v_exp_f32_e32 v179, v179
	v_pk_fma_f32 v[156:157], v[186:187], v[156:157], s[54:55] op_sel_hi:[1,1,0]
	v_pk_fma_f32 v[156:157], v[186:187], v[156:157], s[56:57] op_sel_hi:[1,1,0]
	s_nop 0
	v_pk_mul_f32 v[156:157], v[186:187], v[156:157]
	s_nop 0
	v_pk_mul_f32 v[156:157], v[178:179], v[156:157]
	s_nop 0
	v_max_f32_e32 v178, 0, v176
	v_max_f32_e32 v179, 0, v177
	v_fma_f32 v156, -|v176|, v156, v178
	v_fma_f32 v157, -|v177|, v157, v179
	v_cvt_pk_bf16_f32 v176, v170, v171
	s_nop 0
	v_cvt_pk_bf16_f32 v177, v172, v173
	v_cvt_pk_bf16_f32 v178, v174, v175
	s_nop 1
	s_and_b64 vcc, exec, s[10:11]
	v_cvt_pk_bf16_f32 v179, v156, v157
	global_store_dwordx4 v[182:183], v[176:179], off offset:256
	s_cbranch_vccnz .LBB0_948
	v_mul_f32_e32 v158, v158, v158
	v_fmac_f32_e32 v158, v151, v151
	v_mul_f32_e32 v151, v165, v165
	v_fmac_f32_e32 v151, v159, v159
	v_add_f32_e32 v151, v158, v151
	v_mul_f32_e32 v158, v167, v167
	v_mul_f32_e32 v159, v169, v169
	v_fmac_f32_e32 v158, v166, v166
	v_fmac_f32_e32 v159, v168, v168
	v_add_f32_e32 v158, v158, v159
	v_add_f32_e32 v151, v151, v158
	v_mul_f32_e32 v158, v171, v171
	v_mul_f32_e32 v159, v173, v173
	v_fmac_f32_e32 v158, v170, v170
	v_fmac_f32_e32 v159, v172, v172
	v_add_f32_e32 v158, v158, v159
	v_mul_f32_e32 v159, v175, v175
	v_mul_f32_e32 v157, v157, v157
	v_fmac_f32_e32 v159, v174, v174
	v_fmac_f32_e32 v157, v156, v156
	v_add_f32_e32 v156, v159, v157
	v_add_f32_e32 v156, v158, v156
	v_and_b32_e32 v157, 64, v164
	v_add_f32_e32 v151, v151, v156
	v_xor_b32_e32 v156, 16, v164
	v_add_u32_e32 v157, 64, v157
	v_cmp_lt_i32_e32 vcc, v156, v157
	s_nop 1
	v_cndmask_b32_e32 v156, v164, v156, vcc
	v_lshlrev_b32_e32 v156, 2, v156
	ds_bpermute_b32 v156, v156, v151
	s_waitcnt lgkmcnt(0)
	v_add_f32_e32 v151, v151, v156
	v_xor_b32_e32 v156, 32, v164
	v_cmp_lt_i32_e32 vcc, v156, v157
	s_nop 1
	v_cndmask_b32_e32 v156, v164, v156, vcc
	v_lshlrev_b32_e32 v156, 2, v156
	ds_bpermute_b32 v156, v156, v151
	s_and_saveexec_b64 s[78:79], s[4:5]
	s_cbranch_execz .LBB0_947
	v_lshlrev_b64 v[154:155], 6, v[154:155]
	v_lshl_add_u64 v[154:155], s[18:19], 0, v[154:155]
	v_lshl_add_u64 v[154:155], s[76:77], 2, v[154:155]
	s_lshl_b32 s14, s59, 2
	v_lshl_add_u64 v[154:155], v[154:155], 0, s[14:15]
	s_waitcnt lgkmcnt(0)
	v_add_f32_e32 v151, v151, v156
	global_store_dword v[154:155], v151, off

; __device__ __forceinline__ float dot4(f32x4 v) { return (v[0] * v[0] + v[1] * v[1]) + (v[2] * v[2] + v[3] * v[3]); }
; __device__ __forceinline__ u32x2 pack4(f32x4 v) { u32x2 w; w.x = cvt_pk_bf16(v[0], v[1]); w.y = cvt_pk_bf16(v[2], v[3]); return w; }
; __device__ __forceinline__ float quad_sum(float s) { s += __shfl_xor(s, 16); s += __shfl_xor(s, 32); return s; }
; __device__ __forceinline__ f32x4 gelu4(f32x4 v) { f32x2 a = gelu_pk((f32x2){v[0], v[1]}), b = gelu_pk((f32x2){v[2], v[3]}); return (f32x4){a.x, a.y, b.x, b.y}; }
; __device__ __forceinline__ f32x2 gelu_pk(f32x2 v) {
;     const f32x2 av = __builtin_elementwise_abs(v), d = av * 0.2316418882f + 1.0f;
;     f32x2 t; t.x = __builtin_amdgcn_rcpf(d.x); t.y = __builtin_amdgcn_rcpf(d.y);
;     f32x2 q = t * 0.5307027145f + (-0.7265760135f); q = q * t + 0.7107068705f; q = q * t + (-0.142248368f); q = q * t + 0.127414796f; q = q * t;
;     const f32x2 s = (v * v) * (-0.72134752044f);
;     f32x2 e; e.x = __builtin_amdgcn_exp2f(s.x); e.y = __builtin_amdgcn_exp2f(s.y);
;     const f32x2 m = v * (q * e), r = v - m;
;     f32x2 o; o.x = v.x < 0.f ? m.x : r.x; o.y = v.y < 0.f ? m.y : r.y; return o;
; }
; template <int EK>
; __device__ __forceinline__ void epi_tile(const f32x4 (&acc)[2][2][4][2], const Unit& u, int wr, int wc, int fr, int fq, const EpiArgs& E, const LAS float* rt) {
;     ...
;             } else if (EK == EK_GELU) {
;                 const float r = rr[ai][m]; float ss = 0.f;
; #pragma unroll
;                 for (int bj = 0; bj < 2; ++bj) { const int col = u.pn * BM + bj * HALF + wc * 32 + fq * 8;
;                     const f32x4 z0 = gelu4(acc[ai][bj][m][0] * r), z1 = gelu4(acc[ai][bj][m][1] * r); ss += dot4(z0) + dot4(z1);
;                     const u32x2 lo = pack4(z0), hi = pack4(z1);
;                     *(u32x4*)(E.ob + (size_t)row * E.ldb + col) = (u32x4){lo.x, lo.y, hi.x, hi.y}; }
;                 if (u.pn >= 4) { ss = quad_sum(ss); if (fq == 0) E.stOut[(size_t)row * 16 + (u.pn - 4) * 4 + wc] = ss; }
.LBB0_948:
	v_pk_mul_f32 v[158:159], v[46:47], v[152:153] op_sel_hi:[1,0]
	v_pk_mul_f32 v[168:169], v[48:49], v[152:153] op_sel_hi:[1,0]
	s_waitcnt lgkmcnt(0)
	v_fma_f32 v156, |v158|, s40, 1.0
	v_fma_f32 v157, |v159|, s40, 1.0
	v_pk_mul_f32 v[172:173], v[158:159], v[158:159]
	v_rcp_f32_e32 v166, v156
	v_rcp_f32_e32 v167, v157
	v_mov_b64_e32 v[156:157], s[44:45]
	v_pk_mul_f32 v[172:173], v[172:173], s[58:59] op_sel_hi:[1,0]
	v_pk_fma_f32 v[170:171], v[166:167], s[42:43], v[156:157] op_sel_hi:[1,0,0]
	v_exp_f32_e32 v172, v172
	v_pk_fma_f32 v[170:171], v[166:167], v[170:171], s[52:53] op_sel_hi:[1,1,0]
	v_exp_f32_e32 v173, v173
	v_pk_fma_f32 v[170:171], v[166:167], v[170:171], s[54:55] op_sel_hi:[1,1,0]
	v_pk_fma_f32 v[170:171], v[166:167], v[170:171], s[56:57] op_sel_hi:[1,1,0]
	v_fma_f32 v174, |v168|, s40, 1.0
	v_fma_f32 v175, |v169|, s40, 1.0
	v_pk_mul_f32 v[166:167], v[166:167], v[170:171]
	v_rcp_f32_e32 v174, v174
	v_rcp_f32_e32 v175, v175
	v_pk_mul_f32 v[166:167], v[172:173], v[166:167]
	v_max_f32_e32 v172, 0, v158
	v_max_f32_e32 v173, 0, v159
	v_fma_f32 v151, -|v158|, v166, v172
	v_fma_f32 v158, -|v159|, v167, v173
	v_pk_mul_f32 v[170:171], v[168:169], v[168:169]
	v_pk_mul_f32 v[170:171], v[170:171], s[58:59] op_sel_hi:[1,0]
	v_add_u32_e32 v154, 0x80, v150
	v_pk_fma_f32 v[166:167], v[174:175], s[42:43], v[156:157] op_sel_hi:[1,0,0]
	v_exp_f32_e32 v170, v170
	v_pk_fma_f32 v[166:167], v[174:175], v[166:167], s[52:53] op_sel_hi:[1,1,0]
	v_exp_f32_e32 v171, v171
	v_pk_fma_f32 v[166:167], v[174:175], v[166:167], s[54:55] op_sel_hi:[1,1,0]
	v_pk_mul_f32 v[172:173], v[42:43], v[152:153] op_sel_hi:[1,0]
	v_pk_fma_f32 v[166:167], v[174:175], v[166:167], s[56:57] op_sel_hi:[1,1,0]
	v_pk_mul_f32 v[166:167], v[174:175], v[166:167]
	v_fma_f32 v174, |v172|, s40, 1.0
	v_fma_f32 v175, |v173|, s40, 1.0
	v_pk_mul_f32 v[166:167], v[170:171], v[166:167]
	v_rcp_f32_e32 v174, v174
	v_rcp_f32_e32 v175, v175
	v_max_f32_e32 v170, 0, v168
	v_max_f32_e32 v171, 0, v169
	v_fma_f32 v159, -|v168|, v166, v170
	v_fma_f32 v165, -|v169|, v167, v171
	v_ashrrev_i32_e32 v155, 31, v154
	v_pk_mul_f32 v[168:169], v[44:45], v[152:153] op_sel_hi:[1,0]
	s_nop 0
	v_pk_mul_f32 v[170:171], v[172:173], v[172:173]
	v_pk_fma_f32 v[166:167], v[174:175], s[42:43], v[156:157] op_sel_hi:[1,0,0]
	v_pk_mul_f32 v[170:171], v[170:171], s[58:59] op_sel_hi:[1,0]
	v_pk_fma_f32 v[166:167], v[174:175], v[166:167], s[52:53] op_sel_hi:[1,1,0]
	v_exp_f32_e32 v170, v170
	v_exp_f32_e32 v171, v171
	v_pk_fma_f32 v[166:167], v[174:175], v[166:167], s[54:55] op_sel_hi:[1,1,0]
	v_pk_fma_f32 v[166:167], v[174:175], v[166:167], s[56:57] op_sel_hi:[1,1,0]
	v_fma_f32 v176, |v168|, s40, 1.0
	v_fma_f32 v177, |v169|, s40, 1.0
	v_pk_mul_f32 v[166:167], v[174:175], v[166:167]
	v_rcp_f32_e32 v176, v176
	v_rcp_f32_e32 v177, v177
	v_pk_mul_f32 v[166:167], v[170:171], v[166:167]
	v_max_f32_e32 v170, 0, v172
	v_max_f32_e32 v171, 0, v173
	v_fma_f32 v166, -|v172|, v166, v170
	v_fma_f32 v167, -|v173|, v167, v171
	v_pk_mul_f32 v[174:175], v[168:169], v[168:169]
	v_pk_mul_f32 v[172:173], v[174:175], s[58:59] op_sel_hi:[1,0]
	v_lshlrev_b64 v[174:175], 12, v[154:155]
	v_pk_fma_f32 v[170:171], v[176:177], s[42:43], v[156:157] op_sel_hi:[1,0,0]
	v_exp_f32_e32 v172, v172
	v_pk_fma_f32 v[170:171], v[176:177], v[170:171], s[52:53] op_sel_hi:[1,1,0]
	v_exp_f32_e32 v173, v173
	v_pk_fma_f32 v[170:171], v[176:177], v[170:171], s[54:55] op_sel_hi:[1,1,0]
	v_cmp_gt_f32_e32 vcc, 0, v168
	v_pk_fma_f32 v[170:171], v[176:177], v[170:171], s[56:57] op_sel_hi:[1,1,0]
	v_lshl_add_u64 v[174:175], s[64:65], 0, v[174:175]
	v_pk_mul_f32 v[170:171], v[176:177], v[170:171]
	v_pk_mul_f32 v[176:177], v[14:15], v[152:153] op_sel_hi:[1,0]
	v_pk_mul_f32 v[170:171], v[172:173], v[170:171]
	v_fma_f32 v178, |v176|, s40, 1.0
	v_fma_f32 v179, |v177|, s40, 1.0
	v_pk_mul_f32 v[172:173], v[168:169], v[170:171]
	v_rcp_f32_e32 v178, v178
	v_rcp_f32_e32 v179, v179
	v_pk_fma_f32 v[170:171], v[168:169], v[170:171], v[168:169] neg_lo:[1,0,0] neg_hi:[1,0,0]
	v_lshl_add_u64 v[180:181], v[146:147], 1, v[174:175]
	v_cndmask_b32_e32 v168, v170, v172, vcc
	v_cmp_gt_f32_e32 vcc, 0, v169
	v_cvt_pk_bf16_f32 v170, v151, v158
	v_pk_mul_f32 v[174:175], v[176:177], v[176:177]
	v_cvt_pk_bf16_f32 v172, v166, v167
	s_nop 0
	v_cndmask_b32_e32 v169, v171, v173, vcc
	v_cvt_pk_bf16_f32 v171, v159, v165
	v_cvt_pk_bf16_f32 v173, v168, v169
	global_store_dwordx4 v[180:181], v[170:173], off
	v_pk_mul_f32 v[174:175], v[174:175], s[58:59] op_sel_hi:[1,0]
	v_cmp_gt_f32_e32 vcc, 0, v176
	v_pk_fma_f32 v[170:171], v[178:179], s[42:43], v[156:157] op_sel_hi:[1,0,0]
	v_pk_mul_f32 v[172:173], v[16:17], v[152:153] op_sel_hi:[1,0]
	v_pk_fma_f32 v[170:171], v[178:179], v[170:171], s[52:53] op_sel_hi:[1,1,0]
	v_exp_f32_e32 v174, v174
	v_exp_f32_e32 v175, v175
	v_pk_fma_f32 v[170:171], v[178:179], v[170:171], s[54:55] op_sel_hi:[1,1,0]
	v_pk_fma_f32 v[170:171], v[178:179], v[170:171], s[56:57] op_sel_hi:[1,1,0]
	v_fma_f32 v182, |v172|, s40, 1.0
; __device__ __forceinline__ float dot4(f32x4 v) { return (v[0] * v[0] + v[1] * v[1]) + (v[2] * v[2] + v[3] * v[3]); }
; __device__ __forceinline__ u32x2 pack4(f32x4 v) { u32x2 w; w.x = cvt_pk_bf16(v[0], v[1]); w.y = cvt_pk_bf16(v[2], v[3]); return w; }
; __device__ __forceinline__ float quad_sum(float s) { s += __shfl_xor(s, 16); s += __shfl_xor(s, 32); return s; }
; __device__ __forceinline__ f32x4 gelu4(f32x4 v) { f32x2 a = gelu_pk((f32x2){v[0], v[1]}), b = gelu_pk((f32x2){v[2], v[3]}); return (f32x4){a.x, a.y, b.x, b.y}; }
; __device__ __forceinline__ f32x2 gelu_pk(f32x2 v) {
;     const f32x2 av = __builtin_elementwise_abs(v), d = av * 0.2316418882f + 1.0f;
;     f32x2 t; t.x = __builtin_amdgcn_rcpf(d.x); t.y = __builtin_amdgcn_rcpf(d.y);
;     f32x2 q = t * 0.5307027145f + (-0.7265760135f); q = q * t + 0.7107068705f; q = q * t + (-0.142248368f); q = q * t + 0.127414796f; q = q * t;
;     const f32x2 s = (v * v) * (-0.72134752044f);
;     f32x2 e; e.x = __builtin_amdgcn_exp2f(s.x); e.y = __builtin_amdgcn_exp2f(s.y);
;     const f32x2 m = v * (q * e), r = v - m;
;     f32x2 o; o.x = v.x < 0.f ? m.x : r.x; o.y = v.y < 0.f ? m.y : r.y; return o;
; }
; template <int EK>
; __device__ __forceinline__ void epi_tile(const f32x4 (&acc)[2][2][4][2], const Unit& u, int wr, int wc, int fr, int fq, const EpiArgs& E, const LAS float* rt) {
;     ...
;             } else if (EK == EK_GELU) {
;                 const float r = rr[ai][m]; float ss = 0.f;
; #pragma unroll
;                 for (int bj = 0; bj < 2; ++bj) { const int col = u.pn * BM + bj * HALF + wc * 32 + fq * 8;
;                     const f32x4 z0 = gelu4(acc[ai][bj][m][0] * r), z1 = gelu4(acc[ai][bj][m][1] * r); ss += dot4(z0) + dot4(z1);
;                     const u32x2 lo = pack4(z0), hi = pack4(z1);
;                     *(u32x4*)(E.ob + (size_t)row * E.ldb + col) = (u32x4){lo.x, lo.y, hi.x, hi.y}; }
;                 if (u.pn >= 4) { ss = quad_sum(ss); if (fq == 0) E.stOut[(size_t)row * 16 + (u.pn - 4) * 4 + wc] = ss; }
	v_fma_f32 v183, |v173|, s40, 1.0
	v_pk_mul_f32 v[170:171], v[178:179], v[170:171]
	v_rcp_f32_e32 v182, v182
	v_rcp_f32_e32 v183, v183
	v_pk_mul_f32 v[170:171], v[174:175], v[170:171]
	v_pk_mul_f32 v[178:179], v[172:173], v[172:173]
	v_pk_mul_f32 v[174:175], v[176:177], v[170:171]
	v_pk_fma_f32 v[170:171], v[176:177], v[170:171], v[176:177] neg_lo:[1,0,0] neg_hi:[1,0,0]
	s_nop 0
	v_cndmask_b32_e32 v170, v170, v174, vcc
	v_cmp_gt_f32_e32 vcc, 0, v177
	v_pk_mul_f32 v[176:177], v[178:179], s[58:59] op_sel_hi:[1,0]
	v_pk_mul_f32 v[178:179], v[10:11], v[152:153] op_sel_hi:[1,0]
	v_cndmask_b32_e32 v171, v171, v175, vcc
	v_pk_fma_f32 v[174:175], v[182:183], s[42:43], v[156:157] op_sel_hi:[1,0,0]
	v_exp_f32_e32 v176, v176
	v_pk_fma_f32 v[174:175], v[182:183], v[174:175], s[52:53] op_sel_hi:[1,1,0]
	v_exp_f32_e32 v177, v177
	v_pk_fma_f32 v[174:175], v[182:183], v[174:175], s[54:55] op_sel_hi:[1,1,0]
	v_cmp_gt_f32_e32 vcc, 0, v172
	v_pk_fma_f32 v[174:175], v[182:183], v[174:175], s[56:57] op_sel_hi:[1,1,0]
	v_pk_mul_f32 v[184:185], v[178:179], v[178:179]
	v_pk_mul_f32 v[174:175], v[182:183], v[174:175]
	v_fma_f32 v182, |v178|, s40, 1.0
	v_fma_f32 v183, |v179|, s40, 1.0
	v_pk_mul_f32 v[174:175], v[176:177], v[174:175]
	v_rcp_f32_e32 v182, v182
	v_rcp_f32_e32 v183, v183
	v_pk_mul_f32 v[176:177], v[172:173], v[174:175]
	v_pk_fma_f32 v[174:175], v[172:173], v[174:175], v[172:173] neg_lo:[1,0,0] neg_hi:[1,0,0]
	v_pk_mul_f32 v[184:185], v[184:185], s[58:59] op_sel_hi:[1,0]
	v_cndmask_b32_e32 v172, v174, v176, vcc
	v_cmp_gt_f32_e32 vcc, 0, v173
	v_exp_f32_e32 v184, v184
	v_exp_f32_e32 v185, v185
	v_cndmask_b32_e32 v173, v175, v177, vcc
	v_pk_mul_f32 v[176:177], v[12:13], v[152:153] op_sel_hi:[1,0]
	v_pk_fma_f32 v[174:175], v[182:183], s[42:43], v[156:157] op_sel_hi:[1,0,0]
	v_pk_fma_f32 v[174:175], v[182:183], v[174:175], s[52:53] op_sel_hi:[1,1,0]
	v_pk_fma_f32 v[174:175], v[182:183], v[174:175], s[54:55] op_sel_hi:[1,1,0]
	v_fma_f32 v186, |v176|, s40, 1.0
	v_fma_f32 v187, |v177|, s40, 1.0
	v_pk_fma_f32 v[174:175], v[182:183], v[174:175], s[56:57] op_sel_hi:[1,1,0]
	v_rcp_f32_e32 v186, v186
	v_rcp_f32_e32 v187, v187
	v_pk_mul_f32 v[174:175], v[182:183], v[174:175]
	v_pk_mul_f32 v[182:183], v[176:177], v[176:177]
	v_pk_mul_f32 v[174:175], v[184:185], v[174:175]
	v_max_f32_e32 v184, 0, v178
	v_max_f32_e32 v185, 0, v179
	v_fma_f32 v152, -|v178|, v174, v184
	v_fma_f32 v174, -|v179|, v175, v185
	v_pk_fma_f32 v[156:157], v[186:187], s[42:43], v[156:157] op_sel_hi:[1,0,0]
	v_pk_mul_f32 v[178:179], v[182:183], s[58:59] op_sel_hi:[1,0]
	v_pk_fma_f32 v[156:157], v[186:187], v[156:157], s[52:53] op_sel_hi:[1,1,0]
	v_exp_f32_e32 v178, v178
	v_exp_f32_e32 v179, v179
	v_pk_fma_f32 v[156:157], v[186:187], v[156:157], s[54:55] op_sel_hi:[1,1,0]
	v_pk_fma_f32 v[156:157], v[186:187], v[156:157], s[56:57] op_sel_hi:[1,1,0]
	v_pk_mul_f32 v[156:157], v[186:187], v[156:157]
	s_nop 0
	v_pk_mul_f32 v[156:157], v[178:179], v[156:157]
	s_nop 0
	v_max_f32_e32 v178, 0, v176
	v_max_f32_e32 v179, 0, v177
	v_fma_f32 v156, -|v176|, v156, v178
	v_fma_f32 v157, -|v177|, v157, v179
	v_cvt_pk_bf16_f32 v176, v170, v171
	s_nop 0
	v_cvt_pk_bf16_f32 v177, v172, v173
	v_cvt_pk_bf16_f32 v178, v152, v174
	s_nop 1
	s_and_b64 vcc, exec, s[10:11]
	v_cvt_pk_bf16_f32 v179, v156, v157
	global_store_dwordx4 v[180:181], v[176:179], off offset:256
	s_cbranch_vccnz .LBB0_952
	v_mul_f32_e32 v158, v158, v158
	v_fmac_f32_e32 v158, v151, v151
	v_mul_f32_e32 v151, v165, v165
	v_fmac_f32_e32 v151, v159, v159
	v_add_f32_e32 v151, v158, v151
	v_mul_f32_e32 v158, v167, v167
	v_mul_f32_e32 v159, v169, v169
	v_fmac_f32_e32 v158, v166, v166
	v_fmac_f32_e32 v159, v168, v168
	v_add_f32_e32 v158, v158, v159
	v_add_f32_e32 v151, v151, v158
	v_mul_f32_e32 v158, v171, v171
	v_mul_f32_e32 v159, v173, v173
	v_fmac_f32_e32 v158, v170, v170
	v_fmac_f32_e32 v159, v172, v172
	v_add_f32_e32 v158, v158, v159
	v_mul_f32_e32 v159, v174, v174
	v_fmac_f32_e32 v159, v152, v152
	v_mul_f32_e32 v152, v157, v157
	v_fmac_f32_e32 v152, v156, v156
	v_add_f32_e32 v152, v159, v152
	v_add_f32_e32 v152, v158, v152
	v_and_b32_e32 v156, 64, v164
	v_add_f32_e32 v151, v151, v152
	v_xor_b32_e32 v152, 16, v164
	v_add_u32_e32 v156, 64, v156
	v_cmp_lt_i32_e32 vcc, v152, v156
	s_nop 1
	v_cndmask_b32_e32 v152, v164, v152, vcc
	v_lshlrev_b32_e32 v152, 2, v152
	ds_bpermute_b32 v152, v152, v151
	s_waitcnt lgkmcnt(0)
	v_add_f32_e32 v151, v151, v152
	v_xor_b32_e32 v152, 32, v164
	v_cmp_lt_i32_e32 vcc, v152, v156
	s_nop 1
	v_cndmask_b32_e32 v152, v164, v152, vcc
	v_lshlrev_b32_e32 v152, 2, v152
	ds_bpermute_b32 v152, v152, v151
	s_and_saveexec_b64 s[78:79], s[4:5]
	s_cbranch_execz .LBB0_951
	v_lshlrev_b64 v[154:155], 6, v[154:155]
	v_lshl_add_u64 v[154:155], s[18:19], 0, v[154:155]
	v_lshl_add_u64 v[154:155], s[76:77], 2, v[154:155]
	s_lshl_b32 s14, s59, 2
	v_lshl_add_u64 v[154:155], v[154:155], 0, s[14:15]
	s_waitcnt lgkmcnt(0)
	v_add_f32_e32 v151, v151, v152
	global_store_dword v[154:155], v151, off

; __device__ __forceinline__ float dot4(f32x4 v) { return (v[0] * v[0] + v[1] * v[1]) + (v[2] * v[2] + v[3] * v[3]); }
; __device__ __forceinline__ u32x2 pack4(f32x4 v) { u32x2 w; w.x = cvt_pk_bf16(v[0], v[1]); w.y = cvt_pk_bf16(v[2], v[3]); return w; }
; __device__ __forceinline__ f32x2 gelu_pk(f32x2 v) {
;     const f32x2 av = __builtin_elementwise_abs(v), d = av * 0.2316418882f + 1.0f;
;     f32x2 t; t.x = __builtin_amdgcn_rcpf(d.x); t.y = __builtin_amdgcn_rcpf(d.y);
;     f32x2 q = t * 0.5307027145f + (-0.7265760135f); q = q * t + 0.7107068705f; q = q * t + (-0.142248368f); q = q * t + 0.127414796f; q = q * t;
;     const f32x2 s = (v * v) * (-0.72134752044f);
;     f32x2 e; e.x = __builtin_amdgcn_exp2f(s.x); e.y = __builtin_amdgcn_exp2f(s.y);
;     const f32x2 m = v * (q * e), r = v - m;
;     f32x2 o; o.x = v.x < 0.f ? m.x : r.x; o.y = v.y < 0.f ? m.y : r.y; return o;
; }
; __device__ __forceinline__ f32x4 gelu4(f32x4 v) { f32x2 a = gelu_pk((f32x2){v[0], v[1]}), b = gelu_pk((f32x2){v[2], v[3]}); return (f32x4){a.x, a.y, b.x, b.y}; }
; template <int EK>
; __device__ __forceinline__ void epi_tile(const f32x4 (&acc)[2][2][4][2], const Unit& u, int wr, int wc, int fr, int fq, const EpiArgs& E, const LAS float* rt) {
;     ...
;             } else if (EK == EK_GELU) {
;                 const float r = rr[ai][m]; float ss = 0.f;
; #pragma unroll
;                 for (int bj = 0; bj < 2; ++bj) { const int col = u.pn * BM + bj * HALF + wc * 32 + fq * 8;
;                     const f32x4 z0 = gelu4(acc[ai][bj][m][0] * r), z1 = gelu4(acc[ai][bj][m][1] * r); ss += dot4(z0) + dot4(z1);
;                     const u32x2 lo = pack4(z0), hi = pack4(z1);
;                     *(u32x4*)(E.ob + (size_t)row * E.ldb + col) = (u32x4){lo.x, lo.y, hi.x, hi.y}; }
.LBB0_952:
	v_mov_b32_e32 v172, v153
	v_pk_mul_f32 v[156:157], v[38:39], v[172:173] op_sel_hi:[1,0]
	v_pk_mul_f32 v[166:167], v[40:41], v[172:173] op_sel_hi:[1,0]
	v_fma_f32 v154, |v156|, s40, 1.0
	v_fma_f32 v155, |v157|, s40, 1.0
	v_pk_mul_f32 v[170:171], v[156:157], v[156:157]
	v_rcp_f32_e32 v158, v154
	v_rcp_f32_e32 v159, v155
	v_mov_b64_e32 v[154:155], s[44:45]
	v_pk_mul_f32 v[170:171], v[170:171], s[58:59] op_sel_hi:[1,0]
	v_pk_fma_f32 v[168:169], v[158:159], s[42:43], v[154:155] op_sel_hi:[1,0,0]
	v_exp_f32_e32 v170, v170
	v_pk_fma_f32 v[168:169], v[158:159], v[168:169], s[52:53] op_sel_hi:[1,1,0]
	v_exp_f32_e32 v171, v171
	v_pk_fma_f32 v[168:169], v[158:159], v[168:169], s[54:55] op_sel_hi:[1,1,0]
	v_pk_fma_f32 v[168:169], v[158:159], v[168:169], s[56:57] op_sel_hi:[1,1,0]
	v_fma_f32 v174, |v166|, s40, 1.0
	v_fma_f32 v175, |v167|, s40, 1.0
	v_pk_mul_f32 v[158:159], v[158:159], v[168:169]
	v_rcp_f32_e32 v174, v174
	v_rcp_f32_e32 v175, v175
	v_pk_mul_f32 v[158:159], v[170:171], v[158:159]
	v_max_f32_e32 v170, 0, v156
	v_max_f32_e32 v171, 0, v157
	v_fma_f32 v151, -|v156|, v158, v170
	v_fma_f32 v156, -|v157|, v159, v171
	v_pk_mul_f32 v[168:169], v[166:167], v[166:167]
	v_pk_mul_f32 v[168:169], v[168:169], s[58:59] op_sel_hi:[1,0]
	s_waitcnt lgkmcnt(0)
	v_add_u32_e32 v152, 0x90, v150
	v_pk_fma_f32 v[158:159], v[174:175], s[42:43], v[154:155] op_sel_hi:[1,0,0]
	v_exp_f32_e32 v168, v168
	v_pk_fma_f32 v[158:159], v[174:175], v[158:159], s[52:53] op_sel_hi:[1,1,0]
	v_exp_f32_e32 v169, v169
	v_pk_fma_f32 v[158:159], v[174:175], v[158:159], s[54:55] op_sel_hi:[1,1,0]
	v_pk_mul_f32 v[170:171], v[34:35], v[172:173] op_sel_hi:[1,0]
	v_pk_fma_f32 v[158:159], v[174:175], v[158:159], s[56:57] op_sel_hi:[1,1,0]
	v_pk_mul_f32 v[158:159], v[174:175], v[158:159]
	v_fma_f32 v174, |v170|, s40, 1.0
	v_fma_f32 v175, |v171|, s40, 1.0
	v_pk_mul_f32 v[158:159], v[168:169], v[158:159]
	v_rcp_f32_e32 v174, v174
	v_rcp_f32_e32 v175, v175
	v_max_f32_e32 v168, 0, v166
	v_max_f32_e32 v169, 0, v167
	v_fma_f32 v157, -|v166|, v158, v168
	v_fma_f32 v158, -|v167|, v159, v169
	v_pk_mul_f32 v[176:177], v[170:171], v[170:171]
	v_pk_mul_f32 v[176:177], v[176:177], s[58:59] op_sel_hi:[1,0]
	v_pk_mul_f32 v[166:167], v[36:37], v[172:173] op_sel_hi:[1,0]
	v_pk_fma_f32 v[168:169], v[174:175], s[42:43], v[154:155] op_sel_hi:[1,0,0]
	v_exp_f32_e32 v176, v176
	v_pk_fma_f32 v[168:169], v[174:175], v[168:169], s[52:53] op_sel_hi:[1,1,0]
	v_exp_f32_e32 v177, v177
	v_pk_fma_f32 v[168:169], v[174:175], v[168:169], s[54:55] op_sel_hi:[1,1,0]
	v_pk_fma_f32 v[168:169], v[174:175], v[168:169], s[56:57] op_sel_hi:[1,1,0]
	v_fma_f32 v178, |v166|, s40, 1.0
	v_fma_f32 v179, |v167|, s40, 1.0
	v_pk_mul_f32 v[168:169], v[174:175], v[168:169]
	v_rcp_f32_e32 v178, v178
	v_rcp_f32_e32 v179, v179
	v_pk_mul_f32 v[168:169], v[176:177], v[168:169]
	v_max_f32_e32 v176, 0, v170
	v_max_f32_e32 v177, 0, v171
	v_fma_f32 v159, -|v170|, v168, v176
	v_fma_f32 v165, -|v171|, v169, v177
	v_pk_mul_f32 v[174:175], v[166:167], v[166:167]
	v_pk_mul_f32 v[170:171], v[174:175], s[58:59] op_sel_hi:[1,0]
	v_ashrrev_i32_e32 v153, 31, v152
	v_pk_fma_f32 v[168:169], v[178:179], s[42:43], v[154:155] op_sel_hi:[1,0,0]
	v_exp_f32_e32 v170, v170
	v_pk_fma_f32 v[168:169], v[178:179], v[168:169], s[52:53] op_sel_hi:[1,1,0]
	v_exp_f32_e32 v171, v171
	v_pk_fma_f32 v[168:169], v[178:179], v[168:169], s[54:55] op_sel_hi:[1,1,0]
	v_pk_mul_f32 v[176:177], v[6:7], v[172:173] op_sel_hi:[1,0]
	v_pk_fma_f32 v[168:169], v[178:179], v[168:169], s[56:57] op_sel_hi:[1,1,0]
	v_cmp_gt_f32_e32 vcc, 0, v166
	v_pk_mul_f32 v[168:169], v[178:179], v[168:169]
	v_fma_f32 v178, |v176|, s40, 1.0
	v_fma_f32 v179, |v177|, s40, 1.0
	v_pk_mul_f32 v[168:169], v[170:171], v[168:169]
	v_rcp_f32_e32 v178, v178
	v_rcp_f32_e32 v179, v179
	v_pk_mul_f32 v[170:171], v[166:167], v[168:169]
	v_pk_fma_f32 v[168:169], v[166:167], v[168:169], v[166:167] neg_lo:[1,0,0] neg_hi:[1,0,0]
	v_lshlrev_b64 v[174:175], 12, v[152:153]
	v_cndmask_b32_e32 v166, v168, v170, vcc
	v_cmp_gt_f32_e32 vcc, 0, v167
	v_lshl_add_u64 v[174:175], s[64:65], 0, v[174:175]
	v_cvt_pk_bf16_f32 v168, v151, v156
	v_lshl_add_u64 v[180:181], v[146:147], 1, v[174:175]
	v_cndmask_b32_e32 v167, v169, v171, vcc
	v_cvt_pk_bf16_f32 v169, v157, v158
	v_pk_mul_f32 v[174:175], v[176:177], v[176:177]
	v_cvt_pk_bf16_f32 v170, v159, v165
	v_cvt_pk_bf16_f32 v171, v166, v167
	global_store_dwordx4 v[180:181], v[168:171], off
	v_pk_mul_f32 v[174:175], v[174:175], s[58:59] op_sel_hi:[1,0]
	v_cmp_gt_f32_e32 vcc, 0, v176
	v_pk_fma_f32 v[168:169], v[178:179], s[42:43], v[154:155] op_sel_hi:[1,0,0]
	v_pk_mul_f32 v[170:171], v[8:9], v[172:173] op_sel_hi:[1,0]
	v_pk_fma_f32 v[168:169], v[178:179], v[168:169], s[52:53] op_sel_hi:[1,1,0]
	v_exp_f32_e32 v174, v174
	v_exp_f32_e32 v175, v175
	v_pk_fma_f32 v[168:169], v[178:179], v[168:169], s[54:55] op_sel_hi:[1,1,0]
	v_pk_fma_f32 v[168:169], v[178:179], v[168:169], s[56:57] op_sel_hi:[1,1,0]
	v_fma_f32 v182, |v170|, s40, 1.0
	v_fma_f32 v183, |v171|, s40, 1.0
; __device__ __forceinline__ float dot4(f32x4 v) { return (v[0] * v[0] + v[1] * v[1]) + (v[2] * v[2] + v[3] * v[3]); }
; __device__ __forceinline__ u32x2 pack4(f32x4 v) { u32x2 w; w.x = cvt_pk_bf16(v[0], v[1]); w.y = cvt_pk_bf16(v[2], v[3]); return w; }
; __device__ __forceinline__ float quad_sum(float s) { s += __shfl_xor(s, 16); s += __shfl_xor(s, 32); return s; }
; __device__ __forceinline__ f32x2 gelu_pk(f32x2 v) {
;     const f32x2 av = __builtin_elementwise_abs(v), d = av * 0.2316418882f + 1.0f;
;     f32x2 t; t.x = __builtin_amdgcn_rcpf(d.x); t.y = __builtin_amdgcn_rcpf(d.y);
;     f32x2 q = t * 0.5307027145f + (-0.7265760135f); q = q * t + 0.7107068705f; q = q * t + (-0.142248368f); q = q * t + 0.127414796f; q = q * t;
;     const f32x2 s = (v * v) * (-0.72134752044f);
;     f32x2 e; e.x = __builtin_amdgcn_exp2f(s.x); e.y = __builtin_amdgcn_exp2f(s.y);
;     const f32x2 m = v * (q * e), r = v - m;
;     f32x2 o; o.x = v.x < 0.f ? m.x : r.x; o.y = v.y < 0.f ? m.y : r.y; return o;
; }
; __device__ __forceinline__ f32x4 gelu4(f32x4 v) { f32x2 a = gelu_pk((f32x2){v[0], v[1]}), b = gelu_pk((f32x2){v[2], v[3]}); return (f32x4){a.x, a.y, b.x, b.y}; }
; template <int EK>
; __device__ __forceinline__ void epi_tile(const f32x4 (&acc)[2][2][4][2], const Unit& u, int wr, int wc, int fr, int fq, const EpiArgs& E, const LAS float* rt) {
;     ...
;             } else if (EK == EK_GELU) {
;                 const float r = rr[ai][m]; float ss = 0.f;
; #pragma unroll
;                 for (int bj = 0; bj < 2; ++bj) { const int col = u.pn * BM + bj * HALF + wc * 32 + fq * 8;
;                     const f32x4 z0 = gelu4(acc[ai][bj][m][0] * r), z1 = gelu4(acc[ai][bj][m][1] * r); ss += dot4(z0) + dot4(z1);
;                     const u32x2 lo = pack4(z0), hi = pack4(z1);
;                     *(u32x4*)(E.ob + (size_t)row * E.ldb + col) = (u32x4){lo.x, lo.y, hi.x, hi.y}; }
;                 if (u.pn >= 4) { ss = quad_sum(ss); if (fq == 0) E.stOut[(size_t)row * 16 + (u.pn - 4) * 4 + wc] = ss; }
	v_pk_mul_f32 v[168:169], v[178:179], v[168:169]
	v_rcp_f32_e32 v182, v182
	v_rcp_f32_e32 v183, v183
	v_pk_mul_f32 v[168:169], v[174:175], v[168:169]
	v_pk_mul_f32 v[178:179], v[170:171], v[170:171]
	v_pk_mul_f32 v[174:175], v[176:177], v[168:169]
	v_pk_fma_f32 v[168:169], v[176:177], v[168:169], v[176:177] neg_lo:[1,0,0] neg_hi:[1,0,0]
	s_nop 0
	v_cndmask_b32_e32 v168, v168, v174, vcc
	v_cmp_gt_f32_e32 vcc, 0, v177
	v_pk_mul_f32 v[176:177], v[178:179], s[58:59] op_sel_hi:[1,0]
	v_pk_mul_f32 v[178:179], v[2:3], v[172:173] op_sel_hi:[1,0]
	v_cndmask_b32_e32 v169, v169, v175, vcc
	v_pk_fma_f32 v[174:175], v[182:183], s[42:43], v[154:155] op_sel_hi:[1,0,0]
	v_exp_f32_e32 v176, v176
	v_pk_fma_f32 v[174:175], v[182:183], v[174:175], s[52:53] op_sel_hi:[1,1,0]
	v_exp_f32_e32 v177, v177
	v_pk_fma_f32 v[174:175], v[182:183], v[174:175], s[54:55] op_sel_hi:[1,1,0]
	v_cmp_gt_f32_e32 vcc, 0, v170
	v_pk_fma_f32 v[174:175], v[182:183], v[174:175], s[56:57] op_sel_hi:[1,1,0]
	s_nop 0
	v_pk_mul_f32 v[174:175], v[182:183], v[174:175]
	v_fma_f32 v182, |v178|, s40, 1.0
	v_fma_f32 v183, |v179|, s40, 1.0
	v_pk_mul_f32 v[174:175], v[176:177], v[174:175]
	v_rcp_f32_e32 v182, v182
	v_rcp_f32_e32 v183, v183
	v_pk_mul_f32 v[176:177], v[170:171], v[174:175]
	v_pk_fma_f32 v[174:175], v[170:171], v[174:175], v[170:171] neg_lo:[1,0,0] neg_hi:[1,0,0]
	s_nop 0
	v_cndmask_b32_e32 v170, v174, v176, vcc
	v_cmp_gt_f32_e32 vcc, 0, v171
	s_nop 1
	v_cndmask_b32_e32 v171, v175, v177, vcc
	v_pk_mul_f32 v[176:177], v[178:179], v[178:179]
	v_pk_mul_f32 v[174:175], v[4:5], v[172:173] op_sel_hi:[1,0]
	v_pk_fma_f32 v[172:173], v[182:183], s[42:43], v[154:155] op_sel_hi:[1,0,0]
	v_pk_mul_f32 v[176:177], v[176:177], s[58:59] op_sel_hi:[1,0]
	v_pk_fma_f32 v[172:173], v[182:183], v[172:173], s[52:53] op_sel_hi:[1,1,0]
	v_exp_f32_e32 v176, v176
	v_exp_f32_e32 v177, v177
	v_pk_fma_f32 v[172:173], v[182:183], v[172:173], s[54:55] op_sel_hi:[1,1,0]
	v_pk_fma_f32 v[172:173], v[182:183], v[172:173], s[56:57] op_sel_hi:[1,1,0]
	v_fma_f32 v184, |v174|, s40, 1.0
	v_fma_f32 v185, |v175|, s40, 1.0
	v_pk_mul_f32 v[172:173], v[182:183], v[172:173]
	v_rcp_f32_e32 v184, v184
	v_rcp_f32_e32 v185, v185
	v_pk_mul_f32 v[172:173], v[176:177], v[172:173]
	v_max_f32_e32 v176, 0, v178
	v_max_f32_e32 v177, 0, v179
	v_fma_f32 v172, -|v178|, v172, v176
	v_fma_f32 v173, -|v179|, v173, v177
	v_pk_mul_f32 v[182:183], v[174:175], v[174:175]
	v_pk_fma_f32 v[154:155], v[184:185], s[42:43], v[154:155] op_sel_hi:[1,0,0]
	s_nop 0
	v_pk_mul_f32 v[176:177], v[182:183], s[58:59] op_sel_hi:[1,0]
	v_pk_fma_f32 v[154:155], v[184:185], v[154:155], s[52:53] op_sel_hi:[1,1,0]
	v_exp_f32_e32 v176, v176
	v_exp_f32_e32 v177, v177
	v_pk_fma_f32 v[154:155], v[184:185], v[154:155], s[54:55] op_sel_hi:[1,1,0]
	v_pk_fma_f32 v[154:155], v[184:185], v[154:155], s[56:57] op_sel_hi:[1,1,0]
	s_nop 0
	v_pk_mul_f32 v[154:155], v[184:185], v[154:155]
	s_nop 0
	v_pk_mul_f32 v[154:155], v[176:177], v[154:155]
	s_nop 0
	v_max_f32_e32 v176, 0, v174
	v_max_f32_e32 v177, 0, v175
	v_fma_f32 v154, -|v174|, v154, v176
	v_fma_f32 v155, -|v175|, v155, v177
	v_cvt_pk_bf16_f32 v174, v168, v169
	s_nop 0
	v_cvt_pk_bf16_f32 v175, v170, v171
	v_cvt_pk_bf16_f32 v176, v172, v173
	s_nop 1
	s_and_b64 vcc, exec, s[10:11]
	v_cvt_pk_bf16_f32 v177, v154, v155
	global_store_dwordx4 v[180:181], v[174:177], off offset:256
	s_cbranch_vccnz .LBB0_956
	v_mul_f32_e32 v156, v156, v156
	v_fmac_f32_e32 v156, v151, v151
	v_mul_f32_e32 v151, v158, v158
	v_fmac_f32_e32 v151, v157, v157
	v_add_f32_e32 v151, v156, v151
	v_mul_f32_e32 v156, v165, v165
	v_mul_f32_e32 v157, v167, v167
	v_fmac_f32_e32 v156, v159, v159
	v_fmac_f32_e32 v157, v166, v166
	v_add_f32_e32 v156, v156, v157
	v_add_f32_e32 v151, v151, v156
	v_mul_f32_e32 v156, v169, v169
	v_mul_f32_e32 v157, v171, v171
	v_fmac_f32_e32 v156, v168, v168
	v_fmac_f32_e32 v157, v170, v170
	v_add_f32_e32 v156, v156, v157
	v_mul_f32_e32 v157, v173, v173
	v_mul_f32_e32 v155, v155, v155
	v_fmac_f32_e32 v157, v172, v172
	v_fmac_f32_e32 v155, v154, v154
	v_add_f32_e32 v154, v157, v155
	v_add_f32_e32 v154, v156, v154
	v_and_b32_e32 v155, 64, v164
	v_add_f32_e32 v151, v151, v154
	v_xor_b32_e32 v154, 16, v164
	v_add_u32_e32 v155, 64, v155
	v_cmp_lt_i32_e32 vcc, v154, v155
	s_nop 1
	v_cndmask_b32_e32 v154, v164, v154, vcc
	v_lshlrev_b32_e32 v154, 2, v154
	ds_bpermute_b32 v154, v154, v151
	s_waitcnt lgkmcnt(0)
	v_add_f32_e32 v151, v151, v154
	v_xor_b32_e32 v154, 32, v164
	v_cmp_lt_i32_e32 vcc, v154, v155
	s_nop 1
	v_cndmask_b32_e32 v154, v164, v154, vcc
	v_lshlrev_b32_e32 v154, 2, v154
	ds_bpermute_b32 v154, v154, v151
	s_and_saveexec_b64 s[78:79], s[4:5]
	s_cbranch_execz .LBB0_955
	v_lshlrev_b64 v[152:153], 6, v[152:153]
	v_lshl_add_u64 v[152:153], s[18:19], 0, v[152:153]
	v_lshl_add_u64 v[152:153], s[76:77], 2, v[152:153]
	s_lshl_b32 s14, s59, 2
	v_lshl_add_u64 v[152:153], v[152:153], 0, s[14:15]
	s_waitcnt lgkmcnt(0)
	v_add_f32_e32 v151, v151, v154
	global_store_dword v[152:153], v151, off

; __device__ __forceinline__ float dot4(f32x4 v) { return (v[0] * v[0] + v[1] * v[1]) + (v[2] * v[2] + v[3] * v[3]); }
; __device__ __forceinline__ u32x2 pack4(f32x4 v) { u32x2 w; w.x = cvt_pk_bf16(v[0], v[1]); w.y = cvt_pk_bf16(v[2], v[3]); return w; }
; __device__ __forceinline__ f32x2 gelu_pk(f32x2 v) {
;     const f32x2 av = __builtin_elementwise_abs(v), d = av * 0.2316418882f + 1.0f;
;     f32x2 t; t.x = __builtin_amdgcn_rcpf(d.x); t.y = __builtin_amdgcn_rcpf(d.y);
;     f32x2 q = t * 0.5307027145f + (-0.7265760135f); q = q * t + 0.7107068705f; q = q * t + (-0.142248368f); q = q * t + 0.127414796f; q = q * t;
;     const f32x2 s = (v * v) * (-0.72134752044f);
;     f32x2 e; e.x = __builtin_amdgcn_exp2f(s.x); e.y = __builtin_amdgcn_exp2f(s.y);
;     const f32x2 m = v * (q * e), r = v - m;
;     f32x2 o; o.x = v.x < 0.f ? m.x : r.x; o.y = v.y < 0.f ? m.y : r.y; return o;
; }
; __device__ __forceinline__ f32x4 gelu4(f32x4 v) { f32x2 a = gelu_pk((f32x2){v[0], v[1]}), b = gelu_pk((f32x2){v[2], v[3]}); return (f32x4){a.x, a.y, b.x, b.y}; }
; template <int EK>
; __device__ __forceinline__ void epi_tile(const f32x4 (&acc)[2][2][4][2], const Unit& u, int wr, int wc, int fr, int fq, const EpiArgs& E, const LAS float* rt) {
;     ...
;             } else if (EK == EK_GELU) {
;                 const float r = rr[ai][m]; float ss = 0.f;
; #pragma unroll
;                 for (int bj = 0; bj < 2; ++bj) { const int col = u.pn * BM + bj * HALF + wc * 32 + fq * 8;
;                     const f32x4 z0 = gelu4(acc[ai][bj][m][0] * r), z1 = gelu4(acc[ai][bj][m][1] * r); ss += dot4(z0) + dot4(z1);
;                     const u32x2 lo = pack4(z0), hi = pack4(z1);
;                     *(u32x4*)(E.ob + (size_t)row * E.ldb + col) = (u32x4){lo.x, lo.y, hi.x, hi.y}; }
.LBB0_956:
	v_pk_mul_f32 v[156:157], v[30:31], v[148:149] op_sel_hi:[1,0]
	v_pk_mul_f32 v[166:167], v[32:33], v[148:149] op_sel_hi:[1,0]
	s_waitcnt lgkmcnt(0)
	v_fma_f32 v154, |v156|, s40, 1.0
	v_fma_f32 v155, |v157|, s40, 1.0
	v_pk_mul_f32 v[170:171], v[156:157], v[156:157]
	v_rcp_f32_e32 v158, v154
	v_rcp_f32_e32 v159, v155
	v_mov_b64_e32 v[154:155], s[44:45]
	v_pk_mul_f32 v[170:171], v[170:171], s[58:59] op_sel_hi:[1,0]
	v_pk_fma_f32 v[168:169], v[158:159], s[42:43], v[154:155] op_sel_hi:[1,0,0]
	v_exp_f32_e32 v170, v170
	v_pk_fma_f32 v[168:169], v[158:159], v[168:169], s[52:53] op_sel_hi:[1,1,0]
	v_exp_f32_e32 v171, v171
	v_pk_fma_f32 v[168:169], v[158:159], v[168:169], s[54:55] op_sel_hi:[1,1,0]
	v_pk_fma_f32 v[168:169], v[158:159], v[168:169], s[56:57] op_sel_hi:[1,1,0]
	v_fma_f32 v172, |v166|, s40, 1.0
	v_fma_f32 v173, |v167|, s40, 1.0
	v_pk_mul_f32 v[158:159], v[158:159], v[168:169]
	v_rcp_f32_e32 v172, v172
	v_rcp_f32_e32 v173, v173
	v_pk_mul_f32 v[158:159], v[170:171], v[158:159]
	v_max_f32_e32 v170, 0, v156
	v_max_f32_e32 v171, 0, v157
	v_fma_f32 v151, -|v156|, v158, v170
	v_fma_f32 v156, -|v157|, v159, v171
	v_pk_mul_f32 v[168:169], v[166:167], v[166:167]
	v_pk_mul_f32 v[168:169], v[168:169], s[58:59] op_sel_hi:[1,0]
	v_add_u32_e32 v152, 0xa0, v150
	v_pk_fma_f32 v[158:159], v[172:173], s[42:43], v[154:155] op_sel_hi:[1,0,0]
	v_exp_f32_e32 v168, v168
	v_pk_fma_f32 v[158:159], v[172:173], v[158:159], s[52:53] op_sel_hi:[1,1,0]
	v_exp_f32_e32 v169, v169
	v_pk_fma_f32 v[158:159], v[172:173], v[158:159], s[54:55] op_sel_hi:[1,1,0]
	v_pk_mul_f32 v[170:171], v[26:27], v[148:149] op_sel_hi:[1,0]
	v_pk_fma_f32 v[158:159], v[172:173], v[158:159], s[56:57] op_sel_hi:[1,1,0]
	v_pk_mul_f32 v[158:159], v[172:173], v[158:159]
	v_fma_f32 v172, |v170|, s40, 1.0
	v_fma_f32 v173, |v171|, s40, 1.0
	v_pk_mul_f32 v[158:159], v[168:169], v[158:159]
	v_rcp_f32_e32 v172, v172
	v_rcp_f32_e32 v173, v173
	v_max_f32_e32 v168, 0, v166
	v_max_f32_e32 v169, 0, v167
	v_fma_f32 v157, -|v166|, v158, v168
	v_fma_f32 v158, -|v167|, v159, v169
	v_pk_mul_f32 v[174:175], v[170:171], v[170:171]
	v_pk_mul_f32 v[174:175], v[174:175], s[58:59] op_sel_hi:[1,0]
	v_pk_mul_f32 v[166:167], v[28:29], v[148:149] op_sel_hi:[1,0]
	v_pk_fma_f32 v[168:169], v[172:173], s[42:43], v[154:155] op_sel_hi:[1,0,0]
	v_exp_f32_e32 v174, v174
	v_pk_fma_f32 v[168:169], v[172:173], v[168:169], s[52:53] op_sel_hi:[1,1,0]
	v_exp_f32_e32 v175, v175
	v_pk_fma_f32 v[168:169], v[172:173], v[168:169], s[54:55] op_sel_hi:[1,1,0]
	v_pk_fma_f32 v[168:169], v[172:173], v[168:169], s[56:57] op_sel_hi:[1,1,0]
	v_fma_f32 v176, |v166|, s40, 1.0
	v_fma_f32 v177, |v167|, s40, 1.0
	v_pk_mul_f32 v[168:169], v[172:173], v[168:169]
	v_rcp_f32_e32 v176, v176
	v_rcp_f32_e32 v177, v177
	v_pk_mul_f32 v[168:169], v[174:175], v[168:169]
	v_max_f32_e32 v174, 0, v170
	v_max_f32_e32 v175, 0, v171
	v_fma_f32 v159, -|v170|, v168, v174
	v_fma_f32 v165, -|v171|, v169, v175
	v_pk_mul_f32 v[172:173], v[166:167], v[166:167]
	v_pk_mul_f32 v[170:171], v[172:173], s[58:59] op_sel_hi:[1,0]
	v_ashrrev_i32_e32 v153, 31, v152
	v_pk_fma_f32 v[168:169], v[176:177], s[42:43], v[154:155] op_sel_hi:[1,0,0]
	v_exp_f32_e32 v170, v170
	v_pk_fma_f32 v[168:169], v[176:177], v[168:169], s[52:53] op_sel_hi:[1,1,0]
	v_exp_f32_e32 v171, v171
	v_pk_fma_f32 v[168:169], v[176:177], v[168:169], s[54:55] op_sel_hi:[1,1,0]
	v_pk_mul_f32 v[174:175], v[114:115], v[148:149] op_sel_hi:[1,0]
	v_pk_fma_f32 v[168:169], v[176:177], v[168:169], s[56:57] op_sel_hi:[1,1,0]
	v_cmp_gt_f32_e32 vcc, 0, v166
	v_pk_mul_f32 v[168:169], v[176:177], v[168:169]
	v_fma_f32 v176, |v174|, s40, 1.0
	v_fma_f32 v177, |v175|, s40, 1.0
	v_pk_mul_f32 v[168:169], v[170:171], v[168:169]
	v_rcp_f32_e32 v176, v176
	v_rcp_f32_e32 v177, v177
	v_pk_mul_f32 v[170:171], v[166:167], v[168:169]
	v_pk_fma_f32 v[168:169], v[166:167], v[168:169], v[166:167] neg_lo:[1,0,0] neg_hi:[1,0,0]
	v_lshlrev_b64 v[172:173], 12, v[152:153]
	v_cndmask_b32_e32 v166, v168, v170, vcc
	v_cmp_gt_f32_e32 vcc, 0, v167
	v_lshl_add_u64 v[172:173], s[64:65], 0, v[172:173]
	v_cvt_pk_bf16_f32 v168, v151, v156
	v_lshl_add_u64 v[178:179], v[146:147], 1, v[172:173]
	v_cndmask_b32_e32 v167, v169, v171, vcc
	v_cvt_pk_bf16_f32 v169, v157, v158
	v_pk_mul_f32 v[172:173], v[174:175], v[174:175]
	v_cvt_pk_bf16_f32 v170, v159, v165
	v_cvt_pk_bf16_f32 v171, v166, v167
	global_store_dwordx4 v[178:179], v[168:171], off
	v_pk_mul_f32 v[172:173], v[172:173], s[58:59] op_sel_hi:[1,0]
	v_cmp_gt_f32_e32 vcc, 0, v174
	v_pk_fma_f32 v[168:169], v[176:177], s[42:43], v[154:155] op_sel_hi:[1,0,0]
	v_pk_mul_f32 v[170:171], v[116:117], v[148:149] op_sel_hi:[1,0]
	v_pk_fma_f32 v[168:169], v[176:177], v[168:169], s[52:53] op_sel_hi:[1,1,0]
	v_exp_f32_e32 v172, v172
	v_exp_f32_e32 v173, v173
	v_pk_fma_f32 v[168:169], v[176:177], v[168:169], s[54:55] op_sel_hi:[1,1,0]
	v_pk_fma_f32 v[168:169], v[176:177], v[168:169], s[56:57] op_sel_hi:[1,1,0]
	v_fma_f32 v180, |v170|, s40, 1.0
; __device__ __forceinline__ float dot4(f32x4 v) { return (v[0] * v[0] + v[1] * v[1]) + (v[2] * v[2] + v[3] * v[3]); }
; __device__ __forceinline__ u32x2 pack4(f32x4 v) { u32x2 w; w.x = cvt_pk_bf16(v[0], v[1]); w.y = cvt_pk_bf16(v[2], v[3]); return w; }
; __device__ __forceinline__ float quad_sum(float s) { s += __shfl_xor(s, 16); s += __shfl_xor(s, 32); return s; }
; __device__ __forceinline__ f32x2 gelu_pk(f32x2 v) {
;     const f32x2 av = __builtin_elementwise_abs(v), d = av * 0.2316418882f + 1.0f;
;     f32x2 t; t.x = __builtin_amdgcn_rcpf(d.x); t.y = __builtin_amdgcn_rcpf(d.y);
;     f32x2 q = t * 0.5307027145f + (-0.7265760135f); q = q * t + 0.7107068705f; q = q * t + (-0.142248368f); q = q * t + 0.127414796f; q = q * t;
;     const f32x2 s = (v * v) * (-0.72134752044f);
;     f32x2 e; e.x = __builtin_amdgcn_exp2f(s.x); e.y = __builtin_amdgcn_exp2f(s.y);
;     const f32x2 m = v * (q * e), r = v - m;
;     f32x2 o; o.x = v.x < 0.f ? m.x : r.x; o.y = v.y < 0.f ? m.y : r.y; return o;
; }
; __device__ __forceinline__ f32x4 gelu4(f32x4 v) { f32x2 a = gelu_pk((f32x2){v[0], v[1]}), b = gelu_pk((f32x2){v[2], v[3]}); return (f32x4){a.x, a.y, b.x, b.y}; }
; template <int EK>
; __device__ __forceinline__ void epi_tile(const f32x4 (&acc)[2][2][4][2], const Unit& u, int wr, int wc, int fr, int fq, const EpiArgs& E, const LAS float* rt) {
;     ...
;             } else if (EK == EK_GELU) {
;                 const float r = rr[ai][m]; float ss = 0.f;
; #pragma unroll
;                 for (int bj = 0; bj < 2; ++bj) { const int col = u.pn * BM + bj * HALF + wc * 32 + fq * 8;
;                     const f32x4 z0 = gelu4(acc[ai][bj][m][0] * r), z1 = gelu4(acc[ai][bj][m][1] * r); ss += dot4(z0) + dot4(z1);
;                     const u32x2 lo = pack4(z0), hi = pack4(z1);
;                     *(u32x4*)(E.ob + (size_t)row * E.ldb + col) = (u32x4){lo.x, lo.y, hi.x, hi.y}; }
;                 if (u.pn >= 4) { ss = quad_sum(ss); if (fq == 0) E.stOut[(size_t)row * 16 + (u.pn - 4) * 4 + wc] = ss; }
	v_fma_f32 v181, |v171|, s40, 1.0
	v_pk_mul_f32 v[168:169], v[176:177], v[168:169]
	v_rcp_f32_e32 v180, v180
	v_rcp_f32_e32 v181, v181
	v_pk_mul_f32 v[168:169], v[172:173], v[168:169]
	v_pk_mul_f32 v[176:177], v[170:171], v[170:171]
	v_pk_mul_f32 v[172:173], v[174:175], v[168:169]
	v_pk_fma_f32 v[168:169], v[174:175], v[168:169], v[174:175] neg_lo:[1,0,0] neg_hi:[1,0,0]
	s_nop 0
	v_cndmask_b32_e32 v168, v168, v172, vcc
	v_cmp_gt_f32_e32 vcc, 0, v175
	v_pk_mul_f32 v[174:175], v[176:177], s[58:59] op_sel_hi:[1,0]
	v_pk_mul_f32 v[176:177], v[118:119], v[148:149] op_sel_hi:[1,0]
	v_cndmask_b32_e32 v169, v169, v173, vcc
	v_pk_fma_f32 v[172:173], v[180:181], s[42:43], v[154:155] op_sel_hi:[1,0,0]
	v_exp_f32_e32 v174, v174
	v_pk_fma_f32 v[172:173], v[180:181], v[172:173], s[52:53] op_sel_hi:[1,1,0]
	v_exp_f32_e32 v175, v175
	v_pk_fma_f32 v[172:173], v[180:181], v[172:173], s[54:55] op_sel_hi:[1,1,0]
	v_cmp_gt_f32_e32 vcc, 0, v170
	v_pk_fma_f32 v[172:173], v[180:181], v[172:173], s[56:57] op_sel_hi:[1,1,0]
	v_pk_mul_f32 v[182:183], v[176:177], v[176:177]
	v_pk_mul_f32 v[172:173], v[180:181], v[172:173]
	v_fma_f32 v180, |v176|, s40, 1.0
	v_fma_f32 v181, |v177|, s40, 1.0
	v_pk_mul_f32 v[172:173], v[174:175], v[172:173]
	v_rcp_f32_e32 v180, v180
	v_rcp_f32_e32 v181, v181
	v_pk_mul_f32 v[174:175], v[170:171], v[172:173]
	v_pk_fma_f32 v[172:173], v[170:171], v[172:173], v[170:171] neg_lo:[1,0,0] neg_hi:[1,0,0]
	v_pk_mul_f32 v[182:183], v[182:183], s[58:59] op_sel_hi:[1,0]
	v_cndmask_b32_e32 v170, v172, v174, vcc
	v_cmp_gt_f32_e32 vcc, 0, v171
	v_exp_f32_e32 v182, v182
	v_exp_f32_e32 v183, v183
	v_cndmask_b32_e32 v171, v173, v175, vcc
	v_pk_mul_f32 v[174:175], v[120:121], v[148:149] op_sel_hi:[1,0]
	v_pk_fma_f32 v[172:173], v[180:181], s[42:43], v[154:155] op_sel_hi:[1,0,0]
	v_pk_fma_f32 v[172:173], v[180:181], v[172:173], s[52:53] op_sel_hi:[1,1,0]
	v_pk_fma_f32 v[172:173], v[180:181], v[172:173], s[54:55] op_sel_hi:[1,1,0]
	v_fma_f32 v184, |v174|, s40, 1.0
	v_fma_f32 v185, |v175|, s40, 1.0
	v_pk_fma_f32 v[172:173], v[180:181], v[172:173], s[56:57] op_sel_hi:[1,1,0]
	v_rcp_f32_e32 v184, v184
	v_rcp_f32_e32 v185, v185
	v_pk_mul_f32 v[172:173], v[180:181], v[172:173]
	v_pk_mul_f32 v[180:181], v[174:175], v[174:175]
	v_pk_mul_f32 v[172:173], v[182:183], v[172:173]
	v_max_f32_e32 v182, 0, v176
	v_max_f32_e32 v183, 0, v177
	v_fma_f32 v148, -|v176|, v172, v182
	v_fma_f32 v172, -|v177|, v173, v183
	v_pk_fma_f32 v[154:155], v[184:185], s[42:43], v[154:155] op_sel_hi:[1,0,0]
	v_pk_mul_f32 v[176:177], v[180:181], s[58:59] op_sel_hi:[1,0]
	v_pk_fma_f32 v[154:155], v[184:185], v[154:155], s[52:53] op_sel_hi:[1,1,0]
	v_exp_f32_e32 v176, v176
	v_exp_f32_e32 v177, v177
	v_pk_fma_f32 v[154:155], v[184:185], v[154:155], s[54:55] op_sel_hi:[1,1,0]
	v_pk_fma_f32 v[154:155], v[184:185], v[154:155], s[56:57] op_sel_hi:[1,1,0]
	v_pk_mul_f32 v[154:155], v[184:185], v[154:155]
	s_nop 0
	v_pk_mul_f32 v[154:155], v[176:177], v[154:155]
	s_nop 0
	v_max_f32_e32 v176, 0, v174
	v_max_f32_e32 v177, 0, v175
	v_fma_f32 v154, -|v174|, v154, v176
	v_fma_f32 v155, -|v175|, v155, v177
	v_cvt_pk_bf16_f32 v174, v168, v169
	s_nop 0
	v_cvt_pk_bf16_f32 v175, v170, v171
	v_cvt_pk_bf16_f32 v176, v148, v172
	s_nop 1
	s_and_b64 vcc, exec, s[10:11]
	v_cvt_pk_bf16_f32 v177, v154, v155
	global_store_dwordx4 v[178:179], v[174:177], off offset:256
	s_cbranch_vccnz .LBB0_960
	v_mul_f32_e32 v156, v156, v156
	v_fmac_f32_e32 v156, v151, v151
	v_mul_f32_e32 v151, v158, v158
	v_fmac_f32_e32 v151, v157, v157
	v_add_f32_e32 v151, v156, v151
	v_mul_f32_e32 v156, v165, v165
	v_mul_f32_e32 v157, v167, v167
	v_fmac_f32_e32 v156, v159, v159
	v_fmac_f32_e32 v157, v166, v166
	v_add_f32_e32 v156, v156, v157
	v_add_f32_e32 v151, v151, v156
	v_mul_f32_e32 v156, v169, v169
	v_mul_f32_e32 v157, v171, v171
	v_fmac_f32_e32 v156, v168, v168
	v_fmac_f32_e32 v157, v170, v170
	v_add_f32_e32 v156, v156, v157
	v_mul_f32_e32 v157, v172, v172
	v_fmac_f32_e32 v157, v148, v148
	v_mul_f32_e32 v148, v155, v155
	v_fmac_f32_e32 v148, v154, v154
	v_add_f32_e32 v148, v157, v148
	v_add_f32_e32 v148, v156, v148
	v_and_b32_e32 v154, 64, v164
	v_add_f32_e32 v148, v151, v148
	v_xor_b32_e32 v151, 16, v164
	v_add_u32_e32 v154, 64, v154
	v_cmp_lt_i32_e32 vcc, v151, v154
	s_nop 1
	v_cndmask_b32_e32 v151, v164, v151, vcc
	v_lshlrev_b32_e32 v151, 2, v151
	ds_bpermute_b32 v151, v151, v148
	s_waitcnt lgkmcnt(0)
	v_add_f32_e32 v148, v148, v151
	v_xor_b32_e32 v151, 32, v164
	v_cmp_lt_i32_e32 vcc, v151, v154
	s_nop 1
	v_cndmask_b32_e32 v151, v164, v151, vcc
	v_lshlrev_b32_e32 v151, 2, v151
	ds_bpermute_b32 v151, v151, v148
	s_and_saveexec_b64 s[78:79], s[4:5]
	s_cbranch_execz .LBB0_959
	v_lshlrev_b64 v[152:153], 6, v[152:153]
	v_lshl_add_u64 v[152:153], s[18:19], 0, v[152:153]
	v_lshl_add_u64 v[152:153], s[76:77], 2, v[152:153]
	s_lshl_b32 s14, s59, 2
	v_lshl_add_u64 v[152:153], v[152:153], 0, s[14:15]
	s_waitcnt lgkmcnt(0)
	v_add_f32_e32 v148, v148, v151
	global_store_dword v[152:153], v148, off

; __device__ __forceinline__ float dot4(f32x4 v) { return (v[0] * v[0] + v[1] * v[1]) + (v[2] * v[2] + v[3] * v[3]); }
; __device__ __forceinline__ u32x2 pack4(f32x4 v) { u32x2 w; w.x = cvt_pk_bf16(v[0], v[1]); w.y = cvt_pk_bf16(v[2], v[3]); return w; }
; __device__ __forceinline__ f32x2 gelu_pk(f32x2 v) {
;     const f32x2 av = __builtin_elementwise_abs(v), d = av * 0.2316418882f + 1.0f;
;     f32x2 t; t.x = __builtin_amdgcn_rcpf(d.x); t.y = __builtin_amdgcn_rcpf(d.y);
;     f32x2 q = t * 0.5307027145f + (-0.7265760135f); q = q * t + 0.7107068705f; q = q * t + (-0.142248368f); q = q * t + 0.127414796f; q = q * t;
;     const f32x2 s = (v * v) * (-0.72134752044f);
;     f32x2 e; e.x = __builtin_amdgcn_exp2f(s.x); e.y = __builtin_amdgcn_exp2f(s.y);
;     const f32x2 m = v * (q * e), r = v - m;
;     f32x2 o; o.x = v.x < 0.f ? m.x : r.x; o.y = v.y < 0.f ? m.y : r.y; return o;
; }
; __device__ __forceinline__ f32x4 gelu4(f32x4 v) { f32x2 a = gelu_pk((f32x2){v[0], v[1]}), b = gelu_pk((f32x2){v[2], v[3]}); return (f32x4){a.x, a.y, b.x, b.y}; }
; template <int EK>
; __device__ __forceinline__ void epi_tile(const f32x4 (&acc)[2][2][4][2], const Unit& u, int wr, int wc, int fr, int fq, const EpiArgs& E, const LAS float* rt) {
;     ...
;             } else if (EK == EK_GELU) {
;                 const float r = rr[ai][m]; float ss = 0.f;
; #pragma unroll
;                 for (int bj = 0; bj < 2; ++bj) { const int col = u.pn * BM + bj * HALF + wc * 32 + fq * 8;
;                     const f32x4 z0 = gelu4(acc[ai][bj][m][0] * r), z1 = gelu4(acc[ai][bj][m][1] * r); ss += dot4(z0) + dot4(z1);
;                     const u32x2 lo = pack4(z0), hi = pack4(z1);
;                     *(u32x4*)(E.ob + (size_t)row * E.ldb + col) = (u32x4){lo.x, lo.y, hi.x, hi.y}; }
.LBB0_960:
	v_mov_b32_e32 v170, v149
	v_pk_mul_f32 v[152:153], v[22:23], v[170:171] op_sel_hi:[1,0]
	v_add_u32_e32 v148, 0xb0, v150
	s_waitcnt lgkmcnt(0)
	v_fma_f32 v150, |v152|, s40, 1.0
	v_fma_f32 v151, |v153|, s40, 1.0
	v_pk_mul_f32 v[166:167], v[152:153], v[152:153]
	v_rcp_f32_e32 v154, v150
	v_rcp_f32_e32 v155, v151
	v_mov_b64_e32 v[150:151], s[44:45]
	v_pk_mul_f32 v[166:167], v[166:167], s[58:59] op_sel_hi:[1,0]
	v_pk_mul_f32 v[156:157], v[24:25], v[170:171] op_sel_hi:[1,0]
	v_pk_fma_f32 v[158:159], v[154:155], s[42:43], v[150:151] op_sel_hi:[1,0,0]
	v_exp_f32_e32 v166, v166
	v_pk_fma_f32 v[158:159], v[154:155], v[158:159], s[52:53] op_sel_hi:[1,1,0]
	v_exp_f32_e32 v167, v167
	v_pk_fma_f32 v[158:159], v[154:155], v[158:159], s[54:55] op_sel_hi:[1,1,0]
	v_pk_fma_f32 v[158:159], v[154:155], v[158:159], s[56:57] op_sel_hi:[1,1,0]
	v_fma_f32 v168, |v156|, s40, 1.0
	v_fma_f32 v169, |v157|, s40, 1.0
	v_pk_mul_f32 v[154:155], v[154:155], v[158:159]
	v_rcp_f32_e32 v168, v168
	v_rcp_f32_e32 v169, v169
	v_pk_mul_f32 v[154:155], v[166:167], v[154:155]
	v_cmp_gt_f32_e32 vcc, 0, v152
	v_pk_mul_f32 v[166:167], v[152:153], v[154:155]
	v_pk_fma_f32 v[154:155], v[152:153], v[154:155], v[152:153] neg_lo:[1,0,0] neg_hi:[1,0,0]
	v_pk_mul_f32 v[158:159], v[156:157], v[156:157]
	v_cndmask_b32_e32 v152, v154, v166, vcc
	v_cmp_gt_f32_e32 vcc, 0, v153
	v_pk_mul_f32 v[158:159], v[158:159], s[58:59] op_sel_hi:[1,0]
	v_ashrrev_i32_e32 v149, 31, v148
	v_cndmask_b32_e32 v153, v155, v167, vcc
	v_pk_fma_f32 v[154:155], v[168:169], s[42:43], v[150:151] op_sel_hi:[1,0,0]
	v_exp_f32_e32 v158, v158
	v_pk_fma_f32 v[154:155], v[168:169], v[154:155], s[52:53] op_sel_hi:[1,1,0]
	v_exp_f32_e32 v159, v159
	v_pk_fma_f32 v[154:155], v[168:169], v[154:155], s[54:55] op_sel_hi:[1,1,0]
	v_pk_mul_f32 v[166:167], v[18:19], v[170:171] op_sel_hi:[1,0]
	v_pk_fma_f32 v[154:155], v[168:169], v[154:155], s[56:57] op_sel_hi:[1,1,0]
	v_pk_mul_f32 v[154:155], v[168:169], v[154:155]
	v_fma_f32 v168, |v166|, s40, 1.0
	v_fma_f32 v169, |v167|, s40, 1.0
	v_pk_mul_f32 v[154:155], v[158:159], v[154:155]
	v_rcp_f32_e32 v168, v168
	v_rcp_f32_e32 v169, v169
	v_max_f32_e32 v158, 0, v156
	v_max_f32_e32 v159, 0, v157
	v_fma_f32 v154, -|v156|, v154, v158
	v_fma_f32 v155, -|v157|, v155, v159
	v_pk_mul_f32 v[172:173], v[166:167], v[166:167]
	v_pk_fma_f32 v[156:157], v[168:169], s[42:43], v[150:151] op_sel_hi:[1,0,0]
	v_pk_mul_f32 v[172:173], v[172:173], s[58:59] op_sel_hi:[1,0]
	v_pk_mul_f32 v[158:159], v[20:21], v[170:171] op_sel_hi:[1,0]
	v_pk_fma_f32 v[156:157], v[168:169], v[156:157], s[52:53] op_sel_hi:[1,1,0]
	v_exp_f32_e32 v172, v172
	v_exp_f32_e32 v173, v173
	v_pk_fma_f32 v[156:157], v[168:169], v[156:157], s[54:55] op_sel_hi:[1,1,0]
	v_fma_f32 v174, |v158|, s40, 1.0
	v_fma_f32 v175, |v159|, s40, 1.0
	v_pk_fma_f32 v[156:157], v[168:169], v[156:157], s[56:57] op_sel_hi:[1,1,0]
	v_rcp_f32_e32 v174, v174
	v_rcp_f32_e32 v175, v175
	v_pk_mul_f32 v[156:157], v[168:169], v[156:157]
	v_pk_mul_f32 v[156:157], v[172:173], v[156:157]
	v_pk_mul_f32 v[168:169], v[158:159], v[158:159]
	v_max_f32_e32 v172, 0, v166
	v_max_f32_e32 v173, 0, v167
	v_fma_f32 v156, -|v166|, v156, v172
	v_fma_f32 v157, -|v167|, v157, v173
	v_pk_mul_f32 v[168:169], v[168:169], s[58:59] op_sel_hi:[1,0]
	v_pk_fma_f32 v[166:167], v[174:175], s[42:43], v[150:151] op_sel_hi:[1,0,0]
	v_exp_f32_e32 v168, v168
	v_pk_fma_f32 v[166:167], v[174:175], v[166:167], s[52:53] op_sel_hi:[1,1,0]
	v_exp_f32_e32 v169, v169
	v_pk_fma_f32 v[166:167], v[174:175], v[166:167], s[54:55] op_sel_hi:[1,1,0]
	v_pk_fma_f32 v[166:167], v[174:175], v[166:167], s[56:57] op_sel_hi:[1,1,0]
	v_cmp_gt_f32_e32 vcc, 0, v158
	v_pk_mul_f32 v[166:167], v[174:175], v[166:167]
	v_pk_mul_f32 v[174:175], v[122:123], v[170:171] op_sel_hi:[1,0]
	v_pk_mul_f32 v[166:167], v[168:169], v[166:167]
	v_fma_f32 v176, |v174|, s40, 1.0
	v_fma_f32 v177, |v175|, s40, 1.0
	v_pk_mul_f32 v[168:169], v[158:159], v[166:167]
	v_rcp_f32_e32 v176, v176
	v_rcp_f32_e32 v177, v177
	v_pk_fma_f32 v[166:167], v[158:159], v[166:167], v[158:159] neg_lo:[1,0,0] neg_hi:[1,0,0]
	v_lshlrev_b64 v[172:173], 12, v[148:149]
	v_cndmask_b32_e32 v158, v166, v168, vcc
	v_cmp_gt_f32_e32 vcc, 0, v159
	v_lshl_add_u64 v[172:173], s[64:65], 0, v[172:173]
	v_cvt_pk_bf16_f32 v168, v156, v157
	v_lshl_add_u64 v[178:179], v[146:147], 1, v[172:173]
	v_cndmask_b32_e32 v159, v167, v169, vcc
	v_cvt_pk_bf16_f32 v169, v158, v159
	v_pk_fma_f32 v[146:147], v[176:177], s[42:43], v[150:151] op_sel_hi:[1,0,0]
	v_cvt_pk_bf16_f32 v166, v152, v153
	v_cvt_pk_bf16_f32 v167, v154, v155
	global_store_dwordx4 v[178:179], v[166:169], off
	v_pk_fma_f32 v[146:147], v[176:177], v[146:147], s[52:53] op_sel_hi:[1,1,0]
	v_cmp_gt_f32_e32 vcc, 0, v174
	v_pk_mul_f32 v[168:169], v[174:175], v[174:175]
	v_pk_fma_f32 v[146:147], v[176:177], v[146:147], s[54:55] op_sel_hi:[1,1,0]
	v_pk_mul_f32 v[168:169], v[168:169], s[58:59] op_sel_hi:[1,0]
	v_pk_mul_f32 v[166:167], v[124:125], v[170:171] op_sel_hi:[1,0]
; __device__ __forceinline__ float dot4(f32x4 v) { return (v[0] * v[0] + v[1] * v[1]) + (v[2] * v[2] + v[3] * v[3]); }
; __device__ __forceinline__ u32x2 pack4(f32x4 v) { u32x2 w; w.x = cvt_pk_bf16(v[0], v[1]); w.y = cvt_pk_bf16(v[2], v[3]); return w; }
; __device__ __forceinline__ float quad_sum(float s) { s += __shfl_xor(s, 16); s += __shfl_xor(s, 32); return s; }
; __device__ __forceinline__ f32x2 gelu_pk(f32x2 v) {
;     const f32x2 av = __builtin_elementwise_abs(v), d = av * 0.2316418882f + 1.0f;
;     f32x2 t; t.x = __builtin_amdgcn_rcpf(d.x); t.y = __builtin_amdgcn_rcpf(d.y);
;     f32x2 q = t * 0.5307027145f + (-0.7265760135f); q = q * t + 0.7107068705f; q = q * t + (-0.142248368f); q = q * t + 0.127414796f; q = q * t;
;     const f32x2 s = (v * v) * (-0.72134752044f);
;     f32x2 e; e.x = __builtin_amdgcn_exp2f(s.x); e.y = __builtin_amdgcn_exp2f(s.y);
;     const f32x2 m = v * (q * e), r = v - m;
;     f32x2 o; o.x = v.x < 0.f ? m.x : r.x; o.y = v.y < 0.f ? m.y : r.y; return o;
; }
; __device__ __forceinline__ f32x4 gelu4(f32x4 v) { f32x2 a = gelu_pk((f32x2){v[0], v[1]}), b = gelu_pk((f32x2){v[2], v[3]}); return (f32x4){a.x, a.y, b.x, b.y}; }
; template <int EK>
; __device__ __forceinline__ void epi_tile(const f32x4 (&acc)[2][2][4][2], const Unit& u, int wr, int wc, int fr, int fq, const EpiArgs& E, const LAS float* rt) {
;     ...
;             } else if (EK == EK_GELU) {
;                 const float r = rr[ai][m]; float ss = 0.f;
; #pragma unroll
;                 for (int bj = 0; bj < 2; ++bj) { const int col = u.pn * BM + bj * HALF + wc * 32 + fq * 8;
;                     const f32x4 z0 = gelu4(acc[ai][bj][m][0] * r), z1 = gelu4(acc[ai][bj][m][1] * r); ss += dot4(z0) + dot4(z1);
;                     const u32x2 lo = pack4(z0), hi = pack4(z1);
;                     *(u32x4*)(E.ob + (size_t)row * E.ldb + col) = (u32x4){lo.x, lo.y, hi.x, hi.y}; }
;                 if (u.pn >= 4) { ss = quad_sum(ss); if (fq == 0) E.stOut[(size_t)row * 16 + (u.pn - 4) * 4 + wc] = ss; }
	v_exp_f32_e32 v168, v168
	v_exp_f32_e32 v169, v169
	v_pk_fma_f32 v[146:147], v[176:177], v[146:147], s[56:57] op_sel_hi:[1,1,0]
	v_pk_mul_f32 v[172:173], v[166:167], v[166:167]
	v_pk_mul_f32 v[146:147], v[176:177], v[146:147]
	v_fma_f32 v176, |v166|, s40, 1.0
	v_fma_f32 v177, |v167|, s40, 1.0
	v_pk_mul_f32 v[146:147], v[168:169], v[146:147]
	v_rcp_f32_e32 v176, v176
	v_rcp_f32_e32 v177, v177
	v_pk_mul_f32 v[168:169], v[174:175], v[146:147]
	v_pk_fma_f32 v[146:147], v[174:175], v[146:147], v[174:175] neg_lo:[1,0,0] neg_hi:[1,0,0]
	v_pk_mul_f32 v[172:173], v[172:173], s[58:59] op_sel_hi:[1,0]
	v_cndmask_b32_e32 v146, v146, v168, vcc
	v_cmp_gt_f32_e32 vcc, 0, v175
	v_exp_f32_e32 v172, v172
	v_exp_f32_e32 v173, v173
	v_cndmask_b32_e32 v147, v147, v169, vcc
	v_pk_fma_f32 v[168:169], v[176:177], s[42:43], v[150:151] op_sel_hi:[1,0,0]
	v_pk_mul_f32 v[174:175], v[126:127], v[170:171] op_sel_hi:[1,0]
	v_pk_fma_f32 v[168:169], v[176:177], v[168:169], s[52:53] op_sel_hi:[1,1,0]
	v_pk_fma_f32 v[168:169], v[176:177], v[168:169], s[54:55] op_sel_hi:[1,1,0]
	v_pk_mul_f32 v[170:171], v[128:129], v[170:171] op_sel_hi:[1,0]
	v_pk_fma_f32 v[168:169], v[176:177], v[168:169], s[56:57] op_sel_hi:[1,1,0]
	v_pk_mul_f32 v[168:169], v[176:177], v[168:169]
	v_fma_f32 v176, |v174|, s40, 1.0
	v_fma_f32 v177, |v175|, s40, 1.0
	v_pk_mul_f32 v[168:169], v[172:173], v[168:169]
	v_rcp_f32_e32 v176, v176
	v_rcp_f32_e32 v177, v177
	v_max_f32_e32 v172, 0, v166
	v_max_f32_e32 v173, 0, v167
	v_fma_f32 v165, -|v166|, v168, v172
	v_fma_f32 v166, -|v167|, v169, v173
	v_fma_f32 v180, |v170|, s40, 1.0
	v_fma_f32 v181, |v171|, s40, 1.0
	s_nop 0
	v_pk_mul_f32 v[172:173], v[174:175], v[174:175]
	v_pk_fma_f32 v[168:169], v[176:177], s[42:43], v[150:151] op_sel_hi:[1,0,0]
	v_pk_mul_f32 v[172:173], v[172:173], s[58:59] op_sel_hi:[1,0]
	v_pk_fma_f32 v[168:169], v[176:177], v[168:169], s[52:53] op_sel_hi:[1,1,0]
	v_exp_f32_e32 v172, v172
	v_exp_f32_e32 v173, v173
	v_pk_fma_f32 v[168:169], v[176:177], v[168:169], s[54:55] op_sel_hi:[1,1,0]
	v_rcp_f32_e32 v180, v180
	v_pk_fma_f32 v[168:169], v[176:177], v[168:169], s[56:57] op_sel_hi:[1,1,0]
	v_rcp_f32_e32 v181, v181
	v_pk_mul_f32 v[168:169], v[176:177], v[168:169]
	v_pk_mul_f32 v[168:169], v[172:173], v[168:169]
	v_pk_mul_f32 v[176:177], v[170:171], v[170:171]
	v_max_f32_e32 v172, 0, v174
	v_max_f32_e32 v173, 0, v175
	v_fma_f32 v167, -|v174|, v168, v172
	v_fma_f32 v168, -|v175|, v169, v173
	v_pk_fma_f32 v[150:151], v[180:181], s[42:43], v[150:151] op_sel_hi:[1,0,0]
	v_pk_fma_f32 v[150:151], v[180:181], v[150:151], s[52:53] op_sel_hi:[1,1,0]
	s_nop 0
	v_pk_mul_f32 v[172:173], v[176:177], s[58:59] op_sel_hi:[1,0]
	v_pk_fma_f32 v[150:151], v[180:181], v[150:151], s[54:55] op_sel_hi:[1,1,0]
	v_exp_f32_e32 v172, v172
	v_exp_f32_e32 v173, v173
	v_pk_fma_f32 v[150:151], v[180:181], v[150:151], s[56:57] op_sel_hi:[1,1,0]
	v_pk_mul_f32 v[150:151], v[180:181], v[150:151]
	s_nop 0
	v_pk_mul_f32 v[150:151], v[172:173], v[150:151]
	s_nop 0
	v_max_f32_e32 v172, 0, v170
	v_max_f32_e32 v173, 0, v171
	v_fma_f32 v150, -|v170|, v150, v172
	v_fma_f32 v151, -|v171|, v151, v173
	v_cvt_pk_bf16_f32 v170, v146, v147
	s_nop 0
	v_cvt_pk_bf16_f32 v171, v165, v166
	v_cvt_pk_bf16_f32 v172, v167, v168
	s_nop 1
	s_and_b64 vcc, exec, s[10:11]
	v_cvt_pk_bf16_f32 v173, v150, v151
	global_store_dwordx4 v[178:179], v[170:173], off offset:256
	s_cbranch_vccnz .LBB0_964
	v_mul_f32_e32 v147, v147, v147
	v_fmac_f32_e32 v147, v146, v146
	v_mul_f32_e32 v146, v166, v166
	v_mul_f32_e32 v153, v153, v153
	v_fmac_f32_e32 v146, v165, v165
	v_fmac_f32_e32 v153, v152, v152
	v_mul_f32_e32 v152, v155, v155
	v_add_f32_e32 v146, v147, v146
	v_mul_f32_e32 v147, v168, v168
	v_mul_f32_e32 v151, v151, v151
	v_fmac_f32_e32 v152, v154, v154
	v_fmac_f32_e32 v147, v167, v167
	v_fmac_f32_e32 v151, v150, v150
	v_add_f32_e32 v152, v153, v152
	v_mul_f32_e32 v153, v157, v157
	v_mul_f32_e32 v154, v159, v159
	v_add_f32_e32 v147, v147, v151
	v_and_b32_e32 v150, 64, v164
	v_fmac_f32_e32 v153, v156, v156
	v_fmac_f32_e32 v154, v158, v158
	v_add_f32_e32 v146, v146, v147
	v_xor_b32_e32 v147, 16, v164
	v_add_u32_e32 v150, 64, v150
	v_add_f32_e32 v153, v153, v154
	v_cmp_lt_i32_e32 vcc, v147, v150
	v_add_f32_e32 v152, v152, v153
	v_add_f32_e32 v146, v152, v146
	v_cndmask_b32_e32 v147, v164, v147, vcc
	v_lshlrev_b32_e32 v147, 2, v147
	ds_bpermute_b32 v147, v147, v146
	s_waitcnt lgkmcnt(0)
	v_add_f32_e32 v146, v146, v147
	v_xor_b32_e32 v147, 32, v164
	v_cmp_lt_i32_e32 vcc, v147, v150
	s_nop 1
	v_cndmask_b32_e32 v147, v164, v147, vcc
	v_lshlrev_b32_e32 v147, 2, v147
	ds_bpermute_b32 v147, v147, v146
	s_and_saveexec_b64 s[10:11], s[4:5]
	s_cbranch_execz .LBB0_963
	v_lshlrev_b64 v[148:149], 6, v[148:149]
	v_lshl_add_u64 v[148:149], s[18:19], 0, v[148:149]
	v_lshl_add_u64 v[148:149], s[76:77], 2, v[148:149]
	s_lshl_b32 s14, s59, 2
	v_lshl_add_u64 v[148:149], v[148:149], 0, s[14:15]
	s_waitcnt lgkmcnt(0)
	v_add_f32_e32 v146, v146, v147
	global_store_dword v[148:149], v146, off
